# invariant ds_read base-address registers also in the Wo and QKV K-loops (16 more per-iteration v_add_u32 removed)
# speedup vs baseline: 1.0124x; 1.0010x over previous
; #define PG8_STAGE(bufoff, gbase, voff) do { _Pragma("unroll") for (int _i = 0; _i < 2; ++_i) \
;         __builtin_amdgcn_global_load_lds((const unsigned*)((const char*)(gbase) + (voff)[_i]), (PG8_LAS unsigned*)(lds + (bufoff) + ldsw + _i * 8192), 16, 0, 0); } while (0)
; #define PG8_LDA(dst, b, h) do { _Pragma("unroll") for (int m = 0; m < 4; ++m) _Pragma("unroll") for (int k = 0; k < 2; ++k) dst[m][k] = *(const PG8_LAS bf16x8*)(lds + PG8_SA(b, h) + aoff + m * 2048 + k * 1024); } while (0)
; template <class Epi, class Sched, bool ALIGN_EPI = false, bool SP2 = false>
; __device__ __forceinline__ void gemm_phase(PG8_LAS unsigned char* lds, const Gemm g, const Sched& S, const Epi& E, int wave_s) {
;     ...
;         const char* nA = has_next ? (const char*)g.A + (size_t)nxt.pm * tstepA + (size_t)(nxt.pn / g.npg) * (size_t)(K * 2) : cA; const char* nB = has_next ? (const char*)g.Bt + (size_t)nxt.pn * tstepB : cB;
;         for (int t = 0; t < nt; t += 2) {
;             const bool last = (t == nt - 2);
;             const char* a1 = cA + (size_t)(t + 1) * kstep;
;             const char* a2 = last ? nA : cA + (size_t)(t + 2) * kstep; const char* b2 = last ? nB : cB + (size_t)(t + 2) * kstep;
;             const char* a3 = a2 + kstep; const char* b3 = b2 + kstep;
;             if (last && has_next) S.a_ready(nxt);
;             if constexpr (SP2) {
;             PG8_LDB(B0, 0, 0); PG8_LDB(B1, 0, 1); PG8_SCHED; PG8_LDA(At, 0, 0); PG8_STAGE(PG8_SA(1, 1), a1 + hstepA, voffA);
;             PG8_WAIT_V(8); PG8_WAIT_L(0); PG8_BAR; PG8_MMA(0, 0, At, B0); PG8_MMA(0, 1, At, B1); PG8_BAR; PG8_SCHED;
;             PG8_LDA(At, 0, 1); PG8_STAGE(PG8_SB(0, 0), b2, voffB); PG8_STAGE(PG8_SB(0, 1), b2 + hstepB, voffB); PG8_STAGE(PG8_SA(0, 0), a2, voffA);
;             PG8_WAIT_V(8); PG8_WAIT_L(0); PG8_BAR; PG8_MMA(1, 0, At, B0); PG8_MMA(1, 1, At, B1); PG8_BAR; PG8_SCHED;
;             PG8_LDB(B0, 1, 0); PG8_LDB(B1, 1, 1); PG8_SCHED; PG8_LDA(At, 1, 0); PG8_STAGE(PG8_SA(0, 1), a2 + hstepA, voffA);
;             PG8_WAIT_V(8); PG8_WAIT_L(0); PG8_BAR; PG8_MMA(0, 0, At, B0); PG8_MMA(0, 1, At, B1); PG8_BAR; PG8_SCHED;
;             PG8_LDA(At, 1, 1); PG8_STAGE(PG8_SB(1, 0), b3, voffB); PG8_STAGE(PG8_SB(1, 1), b3 + hstepB, voffB); PG8_STAGE(PG8_SA(1, 0), a3, voffA);
;             PG8_WAIT_V(8); PG8_WAIT_L(0); PG8_BAR; PG8_MMA(1, 0, At, B0); PG8_MMA(1, 1, At, B1); PG8_BAR; PG8_SCHED;
.LBB0_411:
	v_add_u32_e32 v228, 0x10000, v147
	v_add_u32_e32 v229, 0x14000, v147
	v_add_u32_e32 v230, 0x18000, v147
	v_add_u32_e32 v231, 0x1c000, v147
	s_ashr_i32 s15, s14, 31
	s_lshl_b64 s[2:3], s[14:15], 20
	s_add_u32 s28, s22, s2
	s_addc_u32 s29, s23, s3
	s_and_b64 s[2:3], s[4:5], exec
	s_cselect_b32 s2, s29, s31
	s_cselect_b32 s3, s28, s30
	s_add_u32 s4, s40, 0x80080
	s_addc_u32 s5, s41, 0
	s_add_u32 s15, s30, 0x100
	s_addc_u32 s21, s31, 0
	s_mov_b32 s94, -2
	s_add_u32 s30, s4, 0xfff80080
	s_addc_u32 s31, s5, -1
	s_add_i32 s95, 0, 0x10000
	s_cmp_eq_u32 s94, 28
	s_cselect_b32 s41, s27, s31
	s_cselect_b32 s40, s26, s30
	s_cselect_b32 s31, s2, s21
	s_cselect_b32 s30, s3, s15
	s_add_i32 vcc_lo, 0, 0x14000
	ds_read_b128 v[142:145], v228
	ds_read_b128 v[150:153], v228 offset:1024
	ds_read_b128 v[154:157], v228 offset:2048
	ds_read_b128 v[158:161], v228 offset:3072
	ds_read_b128 v[162:165], v229
	ds_read_b128 v[166:169], v229 offset:1024
	ds_read_b128 v[170:173], v229 offset:2048
	ds_read_b128 v[174:177], v229 offset:3072
	s_add_i32 m0, s35, 0xc000
	ds_read_b128 v[178:181], v148
	ds_read_b128 v[182:185], v148 offset:1024
	ds_read_b128 v[186:189], v148 offset:2048
	ds_read_b128 v[190:193], v148 offset:3072
	ds_read_b128 v[194:197], v148 offset:4096
	ds_read_b128 v[198:201], v148 offset:5120
	ds_read_b128 v[202:205], v148 offset:6144
	ds_read_b128 v[206:209], v148 offset:7168
	global_load_lds_dwordx4 v138, s[4:5]
	s_add_i32 m0, s35, 0xe000
	s_nop 0
	global_load_lds_dwordx4 v140, s[4:5]
	s_waitcnt vmcnt(8)
	s_waitcnt lgkmcnt(0)
	s_barrier
	s_waitcnt lgkmcnt(0)
	v_mfma_f32_16x16x32_bf16 v[126:129], v[142:145], v[178:181], 0
	v_mfma_f32_16x16x32_bf16 v[122:125], v[154:157], v[178:181], 0
	v_mfma_f32_16x16x32_bf16 v[110:113], v[142:145], v[186:189], 0
	v_mfma_f32_16x16x32_bf16 v[106:109], v[154:157], v[186:189], 0
	v_mfma_f32_16x16x32_bf16 v[94:97], v[142:145], v[194:197], 0
	v_mfma_f32_16x16x32_bf16 v[90:93], v[154:157], v[194:197], 0
	v_mfma_f32_16x16x32_bf16 v[78:81], v[142:145], v[202:205], 0
	v_mfma_f32_16x16x32_bf16 v[74:77], v[154:157], v[202:205], 0
	v_mfma_f32_16x16x32_bf16 v[126:129], v[150:153], v[182:185], v[126:129]
	v_mfma_f32_16x16x32_bf16 v[122:125], v[158:161], v[182:185], v[122:125]
	v_mfma_f32_16x16x32_bf16 v[110:113], v[150:153], v[190:193], v[110:113]
	v_mfma_f32_16x16x32_bf16 v[106:109], v[158:161], v[190:193], v[106:109]
	v_mfma_f32_16x16x32_bf16 v[94:97], v[150:153], v[198:201], v[94:97]
	v_mfma_f32_16x16x32_bf16 v[90:93], v[158:161], v[198:201], v[90:93]
	v_mfma_f32_16x16x32_bf16 v[78:81], v[150:153], v[206:209], v[78:81]
	v_mfma_f32_16x16x32_bf16 v[74:77], v[158:161], v[206:209], v[74:77]
	v_mfma_f32_16x16x32_bf16 v[118:121], v[162:165], v[178:181], 0
	v_mfma_f32_16x16x32_bf16 v[114:117], v[170:173], v[178:181], 0
	v_mfma_f32_16x16x32_bf16 v[102:105], v[162:165], v[186:189], 0
	v_mfma_f32_16x16x32_bf16 v[98:101], v[170:173], v[186:189], 0
	v_mfma_f32_16x16x32_bf16 v[86:89], v[162:165], v[194:197], 0
	v_mfma_f32_16x16x32_bf16 v[82:85], v[170:173], v[194:197], 0
	v_mfma_f32_16x16x32_bf16 v[70:73], v[162:165], v[202:205], 0
	v_mfma_f32_16x16x32_bf16 v[66:69], v[170:173], v[202:205], 0
	v_mfma_f32_16x16x32_bf16 v[118:121], v[166:169], v[182:185], v[118:121]
	v_mfma_f32_16x16x32_bf16 v[114:117], v[174:177], v[182:185], v[114:117]
	v_mfma_f32_16x16x32_bf16 v[102:105], v[166:169], v[190:193], v[102:105]
	v_mfma_f32_16x16x32_bf16 v[98:101], v[174:177], v[190:193], v[98:101]
	v_mfma_f32_16x16x32_bf16 v[86:89], v[166:169], v[198:201], v[86:89]
	v_mfma_f32_16x16x32_bf16 v[82:85], v[174:177], v[198:201], v[82:85]
	v_mfma_f32_16x16x32_bf16 v[70:73], v[166:169], v[206:209], v[70:73]
	v_mfma_f32_16x16x32_bf16 v[66:69], v[174:177], v[206:209], v[66:69]
	s_barrier
	s_add_i32 s95, s95, s34
	v_lshl_add_u64 v[210:211], s[30:31], 0, v[132:133]
	s_mov_b32 m0, s95
	ds_read_b128 v[178:181], v148 offset:16384
	ds_read_b128 v[182:185], v148 offset:17408
	ds_read_b128 v[186:189], v148 offset:18432
	ds_read_b128 v[190:193], v148 offset:19456
	ds_read_b128 v[194:197], v148 offset:20480
	ds_read_b128 v[198:201], v148 offset:21504
	ds_read_b128 v[202:205], v148 offset:22528
	ds_read_b128 v[206:209], v148 offset:23552
	global_load_lds_dwordx4 v[210:211], off
	s_add_i32 m0, s95, 0x2000
	s_add_u32 s96, s30, 0x80000
	v_lshl_add_u64 v[212:213], s[30:31], 0, v[136:137]
	s_addc_u32 s97, s31, 0
	s_add_i32 s95, vcc_lo, s34
	global_load_lds_dwordx4 v[212:213], off
	s_mov_b32 m0, s95
	v_lshl_add_u64 v[216:217], s[40:41], 0, v[134:135]
	global_load_lds_dwordx4 v132, s[96:97]
	s_add_i32 m0, s95, 0x2000
	s_nop 0
	global_load_lds_dwordx4 v136, s[96:97]
	v_lshl_add_u64 v[214:215], s[40:41], 0, v[130:131]
	s_mov_b32 m0, s35
	s_nop 0
	global_load_lds_dwordx4 v[214:215], off
	s_mov_b32 m0, s36
	s_nop 0
	global_load_lds_dwordx4 v[216:217], off
	s_waitcnt vmcnt(8)
	s_waitcnt lgkmcnt(0)
	s_barrier
; #define PG8_STAGE(bufoff, gbase, voff) do { _Pragma("unroll") for (int _i = 0; _i < 2; ++_i) \
;         __builtin_amdgcn_global_load_lds((const unsigned*)((const char*)(gbase) + (voff)[_i]), (PG8_LAS unsigned*)(lds + (bufoff) + ldsw + _i * 8192), 16, 0, 0); } while (0)
; #define PG8_LDA(dst, b, h) do { _Pragma("unroll") for (int m = 0; m < 4; ++m) _Pragma("unroll") for (int k = 0; k < 2; ++k) dst[m][k] = *(const PG8_LAS bf16x8*)(lds + PG8_SA(b, h) + aoff + m * 2048 + k * 1024); } while (0)
; #define PG8_LDB(dst, b, h) do { _Pragma("unroll") for (int n = 0; n < 2; ++n) _Pragma("unroll") for (int k = 0; k < 2; ++k) dst[n][k] = *(const PG8_LAS bf16x8*)(lds + PG8_SB(b, h) + boff + n * 2048 + k * 1024); } while (0)
; #define PG8_MMA(ai, bj, At, Bt) do { __builtin_amdgcn_s_setprio(1); _Pragma("unroll") for (int m = 0; m < 4; ++m) _Pragma("unroll") for (int n = 0; n < 2; ++n) _Pragma("unroll") for (int k = 0; k < 2; ++k) \
;         acc[ai][bj][m][n] = __builtin_amdgcn_mfma_f32_16x16x32_bf16(Bt[n][k], At[m][k], acc[ai][bj][m][n], 0, 0, 0); __builtin_amdgcn_s_setprio(0); } while (0)
; #define PG8_WAIT_V(n) asm volatile("s_waitcnt vmcnt(" #n ")" ::: "memory")
; #define PG8_WAIT_L(n) asm volatile("s_waitcnt lgkmcnt(" #n ")" ::: "memory")
; #define PG8_BAR __builtin_amdgcn_s_barrier()
; #define PG8_SCHED __builtin_amdgcn_sched_barrier(0)
; template <class Epi, class Sched, bool ALIGN_EPI = false, bool SP2 = false>
; __device__ __forceinline__ void gemm_phase(PG8_LAS unsigned char* lds, const Gemm g, const Sched& S, const Epi& E, int wave_s) {
;     ...
;             PG8_WAIT_V(8); PG8_WAIT_L(0); PG8_BAR; PG8_MMA(1, 0, At, B0); PG8_MMA(1, 1, At, B1); PG8_BAR; PG8_SCHED;
;             PG8_LDB(B0, 1, 0); PG8_LDB(B1, 1, 1); PG8_SCHED; PG8_LDA(At, 1, 0); PG8_STAGE(PG8_SA(0, 1), a2 + hstepA, voffA);
;             PG8_WAIT_V(8); PG8_WAIT_L(0); PG8_BAR; PG8_MMA(0, 0, At, B0); PG8_MMA(0, 1, At, B1); PG8_BAR; PG8_SCHED;
;             PG8_LDA(At, 1, 1); PG8_STAGE(PG8_SB(1, 0), b3, voffB); PG8_STAGE(PG8_SB(1, 1), b3 + hstepB, voffB); PG8_STAGE(PG8_SA(1, 0), a3, voffA);
;             PG8_WAIT_V(8); PG8_WAIT_L(0); PG8_BAR; PG8_MMA(1, 0, At, B0); PG8_MMA(1, 1, At, B1); PG8_BAR; PG8_SCHED;
	s_waitcnt lgkmcnt(0)
	v_mfma_f32_16x16x32_bf16 v[62:65], v[142:145], v[178:181], 0
	v_mfma_f32_16x16x32_bf16 v[58:61], v[154:157], v[178:181], 0
	v_mfma_f32_16x16x32_bf16 v[46:49], v[142:145], v[186:189], 0
	v_mfma_f32_16x16x32_bf16 v[42:45], v[154:157], v[186:189], 0
	v_mfma_f32_16x16x32_bf16 v[30:33], v[142:145], v[194:197], 0
	v_mfma_f32_16x16x32_bf16 v[26:29], v[154:157], v[194:197], 0
	v_mfma_f32_16x16x32_bf16 v[14:17], v[142:145], v[202:205], 0
	v_mfma_f32_16x16x32_bf16 v[10:13], v[154:157], v[202:205], 0
	v_mfma_f32_16x16x32_bf16 v[62:65], v[150:153], v[182:185], v[62:65]
	v_mfma_f32_16x16x32_bf16 v[58:61], v[158:161], v[182:185], v[58:61]
	v_mfma_f32_16x16x32_bf16 v[46:49], v[150:153], v[190:193], v[46:49]
	v_mfma_f32_16x16x32_bf16 v[42:45], v[158:161], v[190:193], v[42:45]
	v_mfma_f32_16x16x32_bf16 v[30:33], v[150:153], v[198:201], v[30:33]
	v_mfma_f32_16x16x32_bf16 v[26:29], v[158:161], v[198:201], v[26:29]
	v_mfma_f32_16x16x32_bf16 v[14:17], v[150:153], v[206:209], v[14:17]
	v_mfma_f32_16x16x32_bf16 v[10:13], v[158:161], v[206:209], v[10:13]
	v_mfma_f32_16x16x32_bf16 v[54:57], v[162:165], v[178:181], 0
	v_mfma_f32_16x16x32_bf16 v[50:53], v[170:173], v[178:181], 0
	v_mfma_f32_16x16x32_bf16 v[38:41], v[162:165], v[186:189], 0
	v_mfma_f32_16x16x32_bf16 v[34:37], v[170:173], v[186:189], 0
	v_mfma_f32_16x16x32_bf16 v[22:25], v[162:165], v[194:197], 0
	v_mfma_f32_16x16x32_bf16 v[18:21], v[170:173], v[194:197], 0
	v_mfma_f32_16x16x32_bf16 v[6:9], v[162:165], v[202:205], 0
	v_mfma_f32_16x16x32_bf16 v[2:5], v[170:173], v[202:205], 0
	v_mfma_f32_16x16x32_bf16 v[54:57], v[166:169], v[182:185], v[54:57]
	v_mfma_f32_16x16x32_bf16 v[50:53], v[174:177], v[182:185], v[50:53]
	v_mfma_f32_16x16x32_bf16 v[38:41], v[166:169], v[190:193], v[38:41]
	v_mfma_f32_16x16x32_bf16 v[34:37], v[174:177], v[190:193], v[34:37]
	v_mfma_f32_16x16x32_bf16 v[22:25], v[166:169], v[198:201], v[22:25]
	v_mfma_f32_16x16x32_bf16 v[18:21], v[174:177], v[198:201], v[18:21]
	v_mfma_f32_16x16x32_bf16 v[6:9], v[166:169], v[206:209], v[6:9]
	v_mfma_f32_16x16x32_bf16 v[2:5], v[174:177], v[206:209], v[2:5]
	s_barrier
	s_add_i32 s95, 0, 0x18000
	s_add_i32 s96, 0, 0x1c000
	ds_read_b128 v[142:145], v230
	ds_read_b128 v[150:153], v230 offset:1024
	ds_read_b128 v[154:157], v230 offset:2048
	ds_read_b128 v[158:161], v230 offset:3072
	ds_read_b128 v[162:165], v231
	ds_read_b128 v[166:169], v231 offset:1024
	ds_read_b128 v[170:173], v231 offset:2048
	ds_read_b128 v[174:177], v231 offset:3072
	s_add_u32 s40, s40, 0x80000
	s_addc_u32 s41, s41, 0
	s_mov_b32 m0, s37
	ds_read_b128 v[178:181], v148 offset:32768
	ds_read_b128 v[182:185], v148 offset:33792
	ds_read_b128 v[186:189], v148 offset:34816
	ds_read_b128 v[190:193], v148 offset:35840
	ds_read_b128 v[194:197], v148 offset:36864
	ds_read_b128 v[198:201], v148 offset:37888
	ds_read_b128 v[202:205], v148 offset:38912
	ds_read_b128 v[206:209], v148 offset:39936
	global_load_lds_dwordx4 v130, s[40:41]
	s_mov_b32 m0, s42
	s_nop 0
	global_load_lds_dwordx4 v134, s[40:41]
	s_waitcnt vmcnt(8)
	s_waitcnt lgkmcnt(0)
	s_barrier
	s_waitcnt lgkmcnt(0)
	v_mfma_f32_16x16x32_bf16 v[126:129], v[142:145], v[178:181], v[126:129]
	v_mfma_f32_16x16x32_bf16 v[122:125], v[154:157], v[178:181], v[122:125]
	v_mfma_f32_16x16x32_bf16 v[110:113], v[142:145], v[186:189], v[110:113]
	v_mfma_f32_16x16x32_bf16 v[106:109], v[154:157], v[186:189], v[106:109]
	v_mfma_f32_16x16x32_bf16 v[94:97], v[142:145], v[194:197], v[94:97]
	v_mfma_f32_16x16x32_bf16 v[90:93], v[154:157], v[194:197], v[90:93]
	v_mfma_f32_16x16x32_bf16 v[78:81], v[142:145], v[202:205], v[78:81]
	v_mfma_f32_16x16x32_bf16 v[74:77], v[154:157], v[202:205], v[74:77]
	v_mfma_f32_16x16x32_bf16 v[126:129], v[150:153], v[182:185], v[126:129]
	v_mfma_f32_16x16x32_bf16 v[122:125], v[158:161], v[182:185], v[122:125]
	v_mfma_f32_16x16x32_bf16 v[110:113], v[150:153], v[190:193], v[110:113]
	v_mfma_f32_16x16x32_bf16 v[106:109], v[158:161], v[190:193], v[106:109]
	v_mfma_f32_16x16x32_bf16 v[94:97], v[150:153], v[198:201], v[94:97]
	v_mfma_f32_16x16x32_bf16 v[90:93], v[158:161], v[198:201], v[90:93]
	v_mfma_f32_16x16x32_bf16 v[78:81], v[150:153], v[206:209], v[78:81]
	v_mfma_f32_16x16x32_bf16 v[74:77], v[158:161], v[206:209], v[74:77]
	v_mfma_f32_16x16x32_bf16 v[118:121], v[162:165], v[178:181], v[118:121]
	v_mfma_f32_16x16x32_bf16 v[114:117], v[170:173], v[178:181], v[114:117]
	v_mfma_f32_16x16x32_bf16 v[102:105], v[162:165], v[186:189], v[102:105]
	v_mfma_f32_16x16x32_bf16 v[98:101], v[170:173], v[186:189], v[98:101]
	v_mfma_f32_16x16x32_bf16 v[86:89], v[162:165], v[194:197], v[86:89]
	v_mfma_f32_16x16x32_bf16 v[82:85], v[170:173], v[194:197], v[82:85]
	v_mfma_f32_16x16x32_bf16 v[70:73], v[162:165], v[202:205], v[70:73]
	v_mfma_f32_16x16x32_bf16 v[66:69], v[170:173], v[202:205], v[66:69]
	v_mfma_f32_16x16x32_bf16 v[118:121], v[166:169], v[182:185], v[118:121]
	v_mfma_f32_16x16x32_bf16 v[114:117], v[174:177], v[182:185], v[114:117]
	v_mfma_f32_16x16x32_bf16 v[102:105], v[166:169], v[190:193], v[102:105]
	v_mfma_f32_16x16x32_bf16 v[98:101], v[174:177], v[190:193], v[98:101]
	v_mfma_f32_16x16x32_bf16 v[86:89], v[166:169], v[198:201], v[86:89]
	v_mfma_f32_16x16x32_bf16 v[82:85], v[174:177], v[198:201], v[82:85]
	v_mfma_f32_16x16x32_bf16 v[70:73], v[166:169], v[206:209], v[70:73]
	v_mfma_f32_16x16x32_bf16 v[66:69], v[174:177], v[206:209], v[66:69]
	s_barrier
; #define PG8_STAGE(bufoff, gbase, voff) do { _Pragma("unroll") for (int _i = 0; _i < 2; ++_i) \
;         __builtin_amdgcn_global_load_lds((const unsigned*)((const char*)(gbase) + (voff)[_i]), (PG8_LAS unsigned*)(lds + (bufoff) + ldsw + _i * 8192), 16, 0, 0); } while (0)
; #define PG8_LDA(dst, b, h) do { _Pragma("unroll") for (int m = 0; m < 4; ++m) _Pragma("unroll") for (int k = 0; k < 2; ++k) dst[m][k] = *(const PG8_LAS bf16x8*)(lds + PG8_SA(b, h) + aoff + m * 2048 + k * 1024); } while (0)
; #define PG8_LDB(dst, b, h) do { _Pragma("unroll") for (int n = 0; n < 2; ++n) _Pragma("unroll") for (int k = 0; k < 2; ++k) dst[n][k] = *(const PG8_LAS bf16x8*)(lds + PG8_SB(b, h) + boff + n * 2048 + k * 1024); } while (0)
; #define PG8_MMA(ai, bj, At, Bt) do { __builtin_amdgcn_s_setprio(1); _Pragma("unroll") for (int m = 0; m < 4; ++m) _Pragma("unroll") for (int n = 0; n < 2; ++n) _Pragma("unroll") for (int k = 0; k < 2; ++k) \
;         acc[ai][bj][m][n] = __builtin_amdgcn_mfma_f32_16x16x32_bf16(Bt[n][k], At[m][k], acc[ai][bj][m][n], 0, 0, 0); __builtin_amdgcn_s_setprio(0); } while (0)
; #define PG8_BAR __builtin_amdgcn_s_barrier()
; template <class Epi, class Sched, bool ALIGN_EPI = false, bool SP2 = false>
; __device__ __forceinline__ void gemm_phase(PG8_LAS unsigned char* lds, const Gemm g, const Sched& S, const Epi& E, int wave_s) {
;     ...
;             PG8_LDB(B0, 0, 0); PG8_LDB(B1, 0, 1); PG8_SCHED; PG8_LDA(At, 0, 0); PG8_STAGE(PG8_SA(1, 1), a1 + hstepA, voffA);
;             PG8_WAIT_V(8); PG8_WAIT_L(0); PG8_BAR; PG8_MMA(0, 0, At, B0); PG8_MMA(0, 1, At, B1); PG8_BAR; PG8_SCHED;
;             PG8_LDA(At, 0, 1); PG8_STAGE(PG8_SB(0, 0), b2, voffB); PG8_STAGE(PG8_SB(0, 1), b2 + hstepB, voffB); PG8_STAGE(PG8_SA(0, 0), a2, voffA);
;             PG8_WAIT_V(8); PG8_WAIT_L(0); PG8_BAR; PG8_MMA(1, 0, At, B0); PG8_MMA(1, 1, At, B1); PG8_BAR; PG8_SCHED;
;             PG8_LDB(B0, 1, 0); PG8_LDB(B1, 1, 1); PG8_SCHED; PG8_LDA(At, 1, 0); PG8_STAGE(PG8_SA(0, 1), a2 + hstepA, voffA);
;             PG8_WAIT_V(8); PG8_WAIT_L(0); PG8_BAR; PG8_MMA(0, 0, At, B0); PG8_MMA(0, 1, At, B1); PG8_BAR; PG8_SCHED;
;             PG8_LDA(At, 1, 1); PG8_STAGE(PG8_SB(1, 0), b3, voffB); PG8_STAGE(PG8_SB(1, 1), b3 + hstepB, voffB); PG8_STAGE(PG8_SA(1, 0), a3, voffA);
;             PG8_WAIT_V(8); PG8_WAIT_L(0); PG8_BAR; PG8_MMA(1, 0, At, B0); PG8_MMA(1, 1, At, B1); PG8_BAR; PG8_SCHED;
	s_add_i32 s40, s95, s34
	v_lshl_add_u64 v[210:211], v[210:211], 0, s[60:61]
	s_mov_b32 m0, s40
	ds_read_b128 v[178:181], v148 offset:49152
	ds_read_b128 v[182:185], v148 offset:50176
	ds_read_b128 v[186:189], v148 offset:51200
	ds_read_b128 v[190:193], v148 offset:52224
	ds_read_b128 v[194:197], v148 offset:53248
	ds_read_b128 v[198:201], v148 offset:54272
	ds_read_b128 v[202:205], v148 offset:55296
	ds_read_b128 v[206:209], v148 offset:56320
	global_load_lds_dwordx4 v[210:211], off
	s_add_i32 m0, s40, 0x2000
	s_add_u32 s30, s30, 0x80080
	v_lshl_add_u64 v[210:211], v[212:213], 0, s[60:61]
	s_addc_u32 s31, s31, 0
	s_add_i32 s40, s96, s34
	global_load_lds_dwordx4 v[210:211], off
	s_mov_b32 m0, s40
	s_nop 0
	global_load_lds_dwordx4 v132, s[30:31]
	s_add_i32 m0, s40, 0x2000
	s_nop 0
	global_load_lds_dwordx4 v136, s[30:31]
	v_lshl_add_u64 v[210:211], v[214:215], 0, s[60:61]
	s_mov_b32 m0, s45
	s_nop 0
	global_load_lds_dwordx4 v[210:211], off
	v_lshl_add_u64 v[210:211], v[216:217], 0, s[60:61]
	s_mov_b32 m0, s46
	s_nop 0
	global_load_lds_dwordx4 v[210:211], off
	s_waitcnt vmcnt(8)
	s_waitcnt lgkmcnt(0)
	s_barrier
	s_waitcnt lgkmcnt(0)
	v_mfma_f32_16x16x32_bf16 v[62:65], v[142:145], v[178:181], v[62:65]
	v_mfma_f32_16x16x32_bf16 v[58:61], v[154:157], v[178:181], v[58:61]
	v_mfma_f32_16x16x32_bf16 v[46:49], v[142:145], v[186:189], v[46:49]
	v_mfma_f32_16x16x32_bf16 v[42:45], v[154:157], v[186:189], v[42:45]
	v_mfma_f32_16x16x32_bf16 v[30:33], v[142:145], v[194:197], v[30:33]
	v_mfma_f32_16x16x32_bf16 v[26:29], v[154:157], v[194:197], v[26:29]
	v_mfma_f32_16x16x32_bf16 v[14:17], v[142:145], v[202:205], v[14:17]
	v_mfma_f32_16x16x32_bf16 v[10:13], v[154:157], v[202:205], v[10:13]
	v_mfma_f32_16x16x32_bf16 v[62:65], v[150:153], v[182:185], v[62:65]
	v_mfma_f32_16x16x32_bf16 v[58:61], v[158:161], v[182:185], v[58:61]
	v_mfma_f32_16x16x32_bf16 v[46:49], v[150:153], v[190:193], v[46:49]
	v_mfma_f32_16x16x32_bf16 v[42:45], v[158:161], v[190:193], v[42:45]
	v_mfma_f32_16x16x32_bf16 v[30:33], v[150:153], v[198:201], v[30:33]
	v_mfma_f32_16x16x32_bf16 v[26:29], v[158:161], v[198:201], v[26:29]
	v_mfma_f32_16x16x32_bf16 v[14:17], v[150:153], v[206:209], v[14:17]
	v_mfma_f32_16x16x32_bf16 v[10:13], v[158:161], v[206:209], v[10:13]
	v_mfma_f32_16x16x32_bf16 v[54:57], v[162:165], v[178:181], v[54:57]
	v_mfma_f32_16x16x32_bf16 v[50:53], v[170:173], v[178:181], v[50:53]
	v_mfma_f32_16x16x32_bf16 v[38:41], v[162:165], v[186:189], v[38:41]
	v_mfma_f32_16x16x32_bf16 v[34:37], v[170:173], v[186:189], v[34:37]
	v_mfma_f32_16x16x32_bf16 v[22:25], v[162:165], v[194:197], v[22:25]
	v_mfma_f32_16x16x32_bf16 v[18:21], v[170:173], v[194:197], v[18:21]
	v_mfma_f32_16x16x32_bf16 v[6:9], v[162:165], v[202:205], v[6:9]
	v_mfma_f32_16x16x32_bf16 v[2:5], v[170:173], v[202:205], v[2:5]
	v_mfma_f32_16x16x32_bf16 v[54:57], v[166:169], v[182:185], v[54:57]
	v_mfma_f32_16x16x32_bf16 v[50:53], v[174:177], v[182:185], v[50:53]
	v_mfma_f32_16x16x32_bf16 v[38:41], v[166:169], v[190:193], v[38:41]
	v_mfma_f32_16x16x32_bf16 v[34:37], v[174:177], v[190:193], v[34:37]
	v_mfma_f32_16x16x32_bf16 v[22:25], v[166:169], v[198:201], v[22:25]
	v_mfma_f32_16x16x32_bf16 v[18:21], v[174:177], v[198:201], v[18:21]
	v_mfma_f32_16x16x32_bf16 v[6:9], v[166:169], v[206:209], v[6:9]
	v_mfma_f32_16x16x32_bf16 v[2:5], v[174:177], v[206:209], v[2:5]
	s_barrier
	s_add_i32 s94, s94, 2
	s_add_u32 s4, s4, 0x100
	s_addc_u32 s5, s5, 0
	s_add_u32 s15, s15, 0x100
	s_addc_u32 s21, s21, 0
	s_cmp_gt_u32 s94, 29
.LBB0_412:
	s_add_u32 s30, s4, 0xfff80080
	s_addc_u32 s31, s5, -1
	s_add_i32 s95, 0, 0x10000
	s_cmp_eq_u32 s94, 28
	s_cselect_b32 s41, s27, s31
	s_cselect_b32 s40, s26, s30
	s_cselect_b32 s31, s2, s21
	s_cselect_b32 s30, s3, s15
	s_add_i32 vcc_lo, 0, 0x14000
	ds_read_b128 v[142:145], v228
	ds_read_b128 v[150:153], v228 offset:1024
	ds_read_b128 v[154:157], v228 offset:2048
	ds_read_b128 v[158:161], v228 offset:3072
	ds_read_b128 v[162:165], v229
	ds_read_b128 v[166:169], v229 offset:1024
	ds_read_b128 v[170:173], v229 offset:2048
	ds_read_b128 v[174:177], v229 offset:3072
	s_add_i32 m0, s35, 0xc000
	ds_read_b128 v[178:181], v148
	ds_read_b128 v[182:185], v148 offset:1024
	ds_read_b128 v[186:189], v148 offset:2048
	ds_read_b128 v[190:193], v148 offset:3072
	ds_read_b128 v[194:197], v148 offset:4096
	ds_read_b128 v[198:201], v148 offset:5120
	ds_read_b128 v[202:205], v148 offset:6144
	ds_read_b128 v[206:209], v148 offset:7168
	global_load_lds_dwordx4 v138, s[4:5]
	s_add_i32 m0, s35, 0xe000
	s_nop 0
	global_load_lds_dwordx4 v140, s[4:5]
	s_waitcnt vmcnt(8)
	s_waitcnt lgkmcnt(0)
	s_barrier
; #define PG8_STAGE(bufoff, gbase, voff) do { _Pragma("unroll") for (int _i = 0; _i < 2; ++_i) \
;         __builtin_amdgcn_global_load_lds((const unsigned*)((const char*)(gbase) + (voff)[_i]), (PG8_LAS unsigned*)(lds + (bufoff) + ldsw + _i * 8192), 16, 0, 0); } while (0)
; #define PG8_LDA(dst, b, h) do { _Pragma("unroll") for (int m = 0; m < 4; ++m) _Pragma("unroll") for (int k = 0; k < 2; ++k) dst[m][k] = *(const PG8_LAS bf16x8*)(lds + PG8_SA(b, h) + aoff + m * 2048 + k * 1024); } while (0)
; #define PG8_LDB(dst, b, h) do { _Pragma("unroll") for (int n = 0; n < 2; ++n) _Pragma("unroll") for (int k = 0; k < 2; ++k) dst[n][k] = *(const PG8_LAS bf16x8*)(lds + PG8_SB(b, h) + boff + n * 2048 + k * 1024); } while (0)
; #define PG8_MMA(ai, bj, At, Bt) do { __builtin_amdgcn_s_setprio(1); _Pragma("unroll") for (int m = 0; m < 4; ++m) _Pragma("unroll") for (int n = 0; n < 2; ++n) _Pragma("unroll") for (int k = 0; k < 2; ++k) \
;         acc[ai][bj][m][n] = __builtin_amdgcn_mfma_f32_16x16x32_bf16(Bt[n][k], At[m][k], acc[ai][bj][m][n], 0, 0, 0); __builtin_amdgcn_s_setprio(0); } while (0)
; #define PG8_WAIT_V(n) asm volatile("s_waitcnt vmcnt(" #n ")" ::: "memory")
; #define PG8_WAIT_L(n) asm volatile("s_waitcnt lgkmcnt(" #n ")" ::: "memory")
; #define PG8_BAR __builtin_amdgcn_s_barrier()
; #define PG8_SCHED __builtin_amdgcn_sched_barrier(0)
; template <class Epi, class Sched, bool ALIGN_EPI = false, bool SP2 = false>
; __device__ __forceinline__ void gemm_phase(PG8_LAS unsigned char* lds, const Gemm g, const Sched& S, const Epi& E, int wave_s) {
;     ...
;             PG8_WAIT_V(8); PG8_WAIT_L(0); PG8_BAR; PG8_MMA(0, 0, At, B0); PG8_MMA(0, 1, At, B1); PG8_BAR; PG8_SCHED;
;             PG8_LDA(At, 0, 1); PG8_STAGE(PG8_SB(0, 0), b2, voffB); PG8_STAGE(PG8_SB(0, 1), b2 + hstepB, voffB); PG8_STAGE(PG8_SA(0, 0), a2, voffA);
;             PG8_WAIT_V(8); PG8_WAIT_L(0); PG8_BAR; PG8_MMA(1, 0, At, B0); PG8_MMA(1, 1, At, B1); PG8_BAR; PG8_SCHED;
;             PG8_LDB(B0, 1, 0); PG8_LDB(B1, 1, 1); PG8_SCHED; PG8_LDA(At, 1, 0); PG8_STAGE(PG8_SA(0, 1), a2 + hstepA, voffA);
;             PG8_WAIT_V(8); PG8_WAIT_L(0); PG8_BAR; PG8_MMA(0, 0, At, B0); PG8_MMA(0, 1, At, B1); PG8_BAR; PG8_SCHED;
	s_waitcnt lgkmcnt(0)
	v_mfma_f32_16x16x32_bf16 v[126:129], v[142:145], v[178:181], v[126:129]
	v_mfma_f32_16x16x32_bf16 v[122:125], v[154:157], v[178:181], v[122:125]
	v_mfma_f32_16x16x32_bf16 v[110:113], v[142:145], v[186:189], v[110:113]
	v_mfma_f32_16x16x32_bf16 v[106:109], v[154:157], v[186:189], v[106:109]
	v_mfma_f32_16x16x32_bf16 v[94:97], v[142:145], v[194:197], v[94:97]
	v_mfma_f32_16x16x32_bf16 v[90:93], v[154:157], v[194:197], v[90:93]
	v_mfma_f32_16x16x32_bf16 v[78:81], v[142:145], v[202:205], v[78:81]
	v_mfma_f32_16x16x32_bf16 v[74:77], v[154:157], v[202:205], v[74:77]
	v_mfma_f32_16x16x32_bf16 v[126:129], v[150:153], v[182:185], v[126:129]
	v_mfma_f32_16x16x32_bf16 v[122:125], v[158:161], v[182:185], v[122:125]
	v_mfma_f32_16x16x32_bf16 v[110:113], v[150:153], v[190:193], v[110:113]
	v_mfma_f32_16x16x32_bf16 v[106:109], v[158:161], v[190:193], v[106:109]
	v_mfma_f32_16x16x32_bf16 v[94:97], v[150:153], v[198:201], v[94:97]
	v_mfma_f32_16x16x32_bf16 v[90:93], v[158:161], v[198:201], v[90:93]
	v_mfma_f32_16x16x32_bf16 v[78:81], v[150:153], v[206:209], v[78:81]
	v_mfma_f32_16x16x32_bf16 v[74:77], v[158:161], v[206:209], v[74:77]
	v_mfma_f32_16x16x32_bf16 v[118:121], v[162:165], v[178:181], v[118:121]
	v_mfma_f32_16x16x32_bf16 v[114:117], v[170:173], v[178:181], v[114:117]
	v_mfma_f32_16x16x32_bf16 v[102:105], v[162:165], v[186:189], v[102:105]
	v_mfma_f32_16x16x32_bf16 v[98:101], v[170:173], v[186:189], v[98:101]
	v_mfma_f32_16x16x32_bf16 v[86:89], v[162:165], v[194:197], v[86:89]
	v_mfma_f32_16x16x32_bf16 v[82:85], v[170:173], v[194:197], v[82:85]
	v_mfma_f32_16x16x32_bf16 v[70:73], v[162:165], v[202:205], v[70:73]
	v_mfma_f32_16x16x32_bf16 v[66:69], v[170:173], v[202:205], v[66:69]
	v_mfma_f32_16x16x32_bf16 v[118:121], v[166:169], v[182:185], v[118:121]
	v_mfma_f32_16x16x32_bf16 v[114:117], v[174:177], v[182:185], v[114:117]
	v_mfma_f32_16x16x32_bf16 v[102:105], v[166:169], v[190:193], v[102:105]
	v_mfma_f32_16x16x32_bf16 v[98:101], v[174:177], v[190:193], v[98:101]
	v_mfma_f32_16x16x32_bf16 v[86:89], v[166:169], v[198:201], v[86:89]
	v_mfma_f32_16x16x32_bf16 v[82:85], v[174:177], v[198:201], v[82:85]
	v_mfma_f32_16x16x32_bf16 v[70:73], v[166:169], v[206:209], v[70:73]
	v_mfma_f32_16x16x32_bf16 v[66:69], v[174:177], v[206:209], v[66:69]
	s_barrier
	s_add_i32 s95, s95, s34
	v_lshl_add_u64 v[210:211], s[30:31], 0, v[132:133]
	s_mov_b32 m0, s95
	ds_read_b128 v[178:181], v148 offset:16384
	ds_read_b128 v[182:185], v148 offset:17408
	ds_read_b128 v[186:189], v148 offset:18432
	ds_read_b128 v[190:193], v148 offset:19456
	ds_read_b128 v[194:197], v148 offset:20480
	ds_read_b128 v[198:201], v148 offset:21504
	ds_read_b128 v[202:205], v148 offset:22528
	ds_read_b128 v[206:209], v148 offset:23552
	global_load_lds_dwordx4 v[210:211], off
	s_add_i32 m0, s95, 0x2000
	s_add_u32 s96, s30, 0x80000
	v_lshl_add_u64 v[212:213], s[30:31], 0, v[136:137]
	s_addc_u32 s97, s31, 0
	s_add_i32 s95, vcc_lo, s34
	global_load_lds_dwordx4 v[212:213], off
	s_mov_b32 m0, s95
	v_lshl_add_u64 v[216:217], s[40:41], 0, v[134:135]
	global_load_lds_dwordx4 v132, s[96:97]
	s_add_i32 m0, s95, 0x2000
	s_nop 0
	global_load_lds_dwordx4 v136, s[96:97]
	v_lshl_add_u64 v[214:215], s[40:41], 0, v[130:131]
	s_mov_b32 m0, s35
	s_nop 0
	global_load_lds_dwordx4 v[214:215], off
	s_mov_b32 m0, s36
	s_nop 0
	global_load_lds_dwordx4 v[216:217], off
	s_waitcnt vmcnt(8)
	s_waitcnt lgkmcnt(0)
	s_barrier
	s_waitcnt lgkmcnt(0)
	v_mfma_f32_16x16x32_bf16 v[62:65], v[142:145], v[178:181], v[62:65]
	v_mfma_f32_16x16x32_bf16 v[58:61], v[154:157], v[178:181], v[58:61]
	v_mfma_f32_16x16x32_bf16 v[46:49], v[142:145], v[186:189], v[46:49]
	v_mfma_f32_16x16x32_bf16 v[42:45], v[154:157], v[186:189], v[42:45]
	v_mfma_f32_16x16x32_bf16 v[30:33], v[142:145], v[194:197], v[30:33]
	v_mfma_f32_16x16x32_bf16 v[26:29], v[154:157], v[194:197], v[26:29]
	v_mfma_f32_16x16x32_bf16 v[14:17], v[142:145], v[202:205], v[14:17]
	v_mfma_f32_16x16x32_bf16 v[10:13], v[154:157], v[202:205], v[10:13]
	v_mfma_f32_16x16x32_bf16 v[62:65], v[150:153], v[182:185], v[62:65]
	v_mfma_f32_16x16x32_bf16 v[58:61], v[158:161], v[182:185], v[58:61]
	v_mfma_f32_16x16x32_bf16 v[46:49], v[150:153], v[190:193], v[46:49]
	v_mfma_f32_16x16x32_bf16 v[42:45], v[158:161], v[190:193], v[42:45]
	v_mfma_f32_16x16x32_bf16 v[30:33], v[150:153], v[198:201], v[30:33]
	v_mfma_f32_16x16x32_bf16 v[26:29], v[158:161], v[198:201], v[26:29]
	v_mfma_f32_16x16x32_bf16 v[14:17], v[150:153], v[206:209], v[14:17]
	v_mfma_f32_16x16x32_bf16 v[10:13], v[158:161], v[206:209], v[10:13]
	v_mfma_f32_16x16x32_bf16 v[54:57], v[162:165], v[178:181], v[54:57]
	v_mfma_f32_16x16x32_bf16 v[50:53], v[170:173], v[178:181], v[50:53]
	v_mfma_f32_16x16x32_bf16 v[38:41], v[162:165], v[186:189], v[38:41]
	v_mfma_f32_16x16x32_bf16 v[34:37], v[170:173], v[186:189], v[34:37]
	v_mfma_f32_16x16x32_bf16 v[22:25], v[162:165], v[194:197], v[22:25]
	v_mfma_f32_16x16x32_bf16 v[18:21], v[170:173], v[194:197], v[18:21]
	v_mfma_f32_16x16x32_bf16 v[6:9], v[162:165], v[202:205], v[6:9]
	v_mfma_f32_16x16x32_bf16 v[2:5], v[170:173], v[202:205], v[2:5]
	v_mfma_f32_16x16x32_bf16 v[54:57], v[166:169], v[182:185], v[54:57]
	v_mfma_f32_16x16x32_bf16 v[50:53], v[174:177], v[182:185], v[50:53]
	v_mfma_f32_16x16x32_bf16 v[38:41], v[166:169], v[190:193], v[38:41]
	v_mfma_f32_16x16x32_bf16 v[34:37], v[174:177], v[190:193], v[34:37]
	v_mfma_f32_16x16x32_bf16 v[22:25], v[166:169], v[198:201], v[22:25]
	v_mfma_f32_16x16x32_bf16 v[18:21], v[174:177], v[198:201], v[18:21]
	v_mfma_f32_16x16x32_bf16 v[6:9], v[166:169], v[206:209], v[6:9]
	v_mfma_f32_16x16x32_bf16 v[2:5], v[174:177], v[206:209], v[2:5]
	s_barrier
; #define PG8_STAGE(bufoff, gbase, voff) do { _Pragma("unroll") for (int _i = 0; _i < 2; ++_i) \
;         __builtin_amdgcn_global_load_lds((const unsigned*)((const char*)(gbase) + (voff)[_i]), (PG8_LAS unsigned*)(lds + (bufoff) + ldsw + _i * 8192), 16, 0, 0); } while (0)
; #define PG8_LDA(dst, b, h) do { _Pragma("unroll") for (int m = 0; m < 4; ++m) _Pragma("unroll") for (int k = 0; k < 2; ++k) dst[m][k] = *(const PG8_LAS bf16x8*)(lds + PG8_SA(b, h) + aoff + m * 2048 + k * 1024); } while (0)
; #define PG8_LDB(dst, b, h) do { _Pragma("unroll") for (int n = 0; n < 2; ++n) _Pragma("unroll") for (int k = 0; k < 2; ++k) dst[n][k] = *(const PG8_LAS bf16x8*)(lds + PG8_SB(b, h) + boff + n * 2048 + k * 1024); } while (0)
; #define PG8_MMA(ai, bj, At, Bt) do { __builtin_amdgcn_s_setprio(1); _Pragma("unroll") for (int m = 0; m < 4; ++m) _Pragma("unroll") for (int n = 0; n < 2; ++n) _Pragma("unroll") for (int k = 0; k < 2; ++k) \
;         acc[ai][bj][m][n] = __builtin_amdgcn_mfma_f32_16x16x32_bf16(Bt[n][k], At[m][k], acc[ai][bj][m][n], 0, 0, 0); __builtin_amdgcn_s_setprio(0); } while (0)
; #define PG8_WAIT_V(n) asm volatile("s_waitcnt vmcnt(" #n ")" ::: "memory")
; #define PG8_WAIT_L(n) asm volatile("s_waitcnt lgkmcnt(" #n ")" ::: "memory")
; #define PG8_BAR __builtin_amdgcn_s_barrier()
; #define PG8_SCHED __builtin_amdgcn_sched_barrier(0)
; template <class Epi, class Sched, bool ALIGN_EPI = false, bool SP2 = false>
; __device__ __forceinline__ void gemm_phase(PG8_LAS unsigned char* lds, const Gemm g, const Sched& S, const Epi& E, int wave_s) {
;     ...
;             PG8_LDB(B0, 1, 0); PG8_LDB(B1, 1, 1); PG8_SCHED; PG8_LDA(At, 1, 0); PG8_STAGE(PG8_SA(0, 1), a2 + hstepA, voffA);
;             PG8_WAIT_V(8); PG8_WAIT_L(0); PG8_BAR; PG8_MMA(0, 0, At, B0); PG8_MMA(0, 1, At, B1); PG8_BAR; PG8_SCHED;
;             PG8_LDA(At, 1, 1); PG8_STAGE(PG8_SB(1, 0), b3, voffB); PG8_STAGE(PG8_SB(1, 1), b3 + hstepB, voffB); PG8_STAGE(PG8_SA(1, 0), a3, voffA);
;             PG8_WAIT_V(8); PG8_WAIT_L(0); PG8_BAR; PG8_MMA(1, 0, At, B0); PG8_MMA(1, 1, At, B1); PG8_BAR; PG8_SCHED;
	s_add_i32 s95, 0, 0x18000
	s_add_i32 s96, 0, 0x1c000
	ds_read_b128 v[142:145], v230
	ds_read_b128 v[150:153], v230 offset:1024
	ds_read_b128 v[154:157], v230 offset:2048
	ds_read_b128 v[158:161], v230 offset:3072
	ds_read_b128 v[162:165], v231
	ds_read_b128 v[166:169], v231 offset:1024
	ds_read_b128 v[170:173], v231 offset:2048
	ds_read_b128 v[174:177], v231 offset:3072
	s_add_u32 s40, s40, 0x80000
	s_addc_u32 s41, s41, 0
	s_mov_b32 m0, s37
	ds_read_b128 v[178:181], v148 offset:32768
	ds_read_b128 v[182:185], v148 offset:33792
	ds_read_b128 v[186:189], v148 offset:34816
	ds_read_b128 v[190:193], v148 offset:35840
	ds_read_b128 v[194:197], v148 offset:36864
	ds_read_b128 v[198:201], v148 offset:37888
	ds_read_b128 v[202:205], v148 offset:38912
	ds_read_b128 v[206:209], v148 offset:39936
	global_load_lds_dwordx4 v130, s[40:41]
	v_lshl_add_u64 v[218:219], s[40:41], 0, v[134:135]
	s_mov_b32 m0, s42
	s_nop 0
	global_load_lds_dwordx4 v[218:219], off
	s_waitcnt vmcnt(8)
	s_waitcnt lgkmcnt(0)
	s_barrier
	s_waitcnt lgkmcnt(0)
	v_mfma_f32_16x16x32_bf16 v[126:129], v[142:145], v[178:181], v[126:129]
	v_mfma_f32_16x16x32_bf16 v[122:125], v[154:157], v[178:181], v[122:125]
	v_mfma_f32_16x16x32_bf16 v[110:113], v[142:145], v[186:189], v[110:113]
	v_mfma_f32_16x16x32_bf16 v[106:109], v[154:157], v[186:189], v[106:109]
	v_mfma_f32_16x16x32_bf16 v[94:97], v[142:145], v[194:197], v[94:97]
	v_mfma_f32_16x16x32_bf16 v[90:93], v[154:157], v[194:197], v[90:93]
	v_mfma_f32_16x16x32_bf16 v[78:81], v[142:145], v[202:205], v[78:81]
	v_mfma_f32_16x16x32_bf16 v[74:77], v[154:157], v[202:205], v[74:77]
	v_mfma_f32_16x16x32_bf16 v[126:129], v[150:153], v[182:185], v[126:129]
	v_mfma_f32_16x16x32_bf16 v[122:125], v[158:161], v[182:185], v[122:125]
	v_mfma_f32_16x16x32_bf16 v[110:113], v[150:153], v[190:193], v[110:113]
	v_mfma_f32_16x16x32_bf16 v[106:109], v[158:161], v[190:193], v[106:109]
	v_mfma_f32_16x16x32_bf16 v[94:97], v[150:153], v[198:201], v[94:97]
	v_mfma_f32_16x16x32_bf16 v[90:93], v[158:161], v[198:201], v[90:93]
	v_mfma_f32_16x16x32_bf16 v[78:81], v[150:153], v[206:209], v[78:81]
	v_mfma_f32_16x16x32_bf16 v[74:77], v[158:161], v[206:209], v[74:77]
	v_mfma_f32_16x16x32_bf16 v[118:121], v[162:165], v[178:181], v[118:121]
	v_mfma_f32_16x16x32_bf16 v[114:117], v[170:173], v[178:181], v[114:117]
	v_mfma_f32_16x16x32_bf16 v[102:105], v[162:165], v[186:189], v[102:105]
	v_mfma_f32_16x16x32_bf16 v[98:101], v[170:173], v[186:189], v[98:101]
	v_mfma_f32_16x16x32_bf16 v[86:89], v[162:165], v[194:197], v[86:89]
	v_mfma_f32_16x16x32_bf16 v[82:85], v[170:173], v[194:197], v[82:85]
	v_mfma_f32_16x16x32_bf16 v[70:73], v[162:165], v[202:205], v[70:73]
	v_mfma_f32_16x16x32_bf16 v[66:69], v[170:173], v[202:205], v[66:69]
	v_mfma_f32_16x16x32_bf16 v[118:121], v[166:169], v[182:185], v[118:121]
	v_mfma_f32_16x16x32_bf16 v[114:117], v[174:177], v[182:185], v[114:117]
	v_mfma_f32_16x16x32_bf16 v[102:105], v[166:169], v[190:193], v[102:105]
	v_mfma_f32_16x16x32_bf16 v[98:101], v[174:177], v[190:193], v[98:101]
	v_mfma_f32_16x16x32_bf16 v[86:89], v[166:169], v[198:201], v[86:89]
	v_mfma_f32_16x16x32_bf16 v[82:85], v[174:177], v[198:201], v[82:85]
	v_mfma_f32_16x16x32_bf16 v[70:73], v[166:169], v[206:209], v[70:73]
	v_mfma_f32_16x16x32_bf16 v[66:69], v[174:177], v[206:209], v[66:69]
	s_barrier
	s_add_i32 s40, s95, s34
	v_lshl_add_u64 v[210:211], v[210:211], 0, s[60:61]
	s_mov_b32 m0, s40
	ds_read_b128 v[178:181], v148 offset:49152
	ds_read_b128 v[182:185], v148 offset:50176
	ds_read_b128 v[186:189], v148 offset:51200
	ds_read_b128 v[190:193], v148 offset:52224
	ds_read_b128 v[194:197], v148 offset:53248
	ds_read_b128 v[198:201], v148 offset:54272
	ds_read_b128 v[202:205], v148 offset:55296
	ds_read_b128 v[206:209], v148 offset:56320
	global_load_lds_dwordx4 v[210:211], off
	s_add_i32 m0, s40, 0x2000
	s_add_u32 s30, s30, 0x80080
	v_lshl_add_u64 v[210:211], v[212:213], 0, s[60:61]
	s_addc_u32 s31, s31, 0
	s_add_i32 s40, s96, s34
	global_load_lds_dwordx4 v[210:211], off
	s_mov_b32 m0, s40
	s_nop 0
	global_load_lds_dwordx4 v132, s[30:31]
	s_add_i32 m0, s40, 0x2000
	s_nop 0
	global_load_lds_dwordx4 v136, s[30:31]
	v_lshl_add_u64 v[210:211], v[214:215], 0, s[60:61]
	s_mov_b32 m0, s45
	s_nop 0
	global_load_lds_dwordx4 v[210:211], off
	v_lshl_add_u64 v[210:211], v[216:217], 0, s[60:61]
	s_mov_b32 m0, s46
	s_nop 0
	global_load_lds_dwordx4 v[210:211], off
	s_waitcnt vmcnt(8)
	s_waitcnt lgkmcnt(0)
	s_barrier
	s_waitcnt lgkmcnt(0)
	v_mfma_f32_16x16x32_bf16 v[62:65], v[142:145], v[178:181], v[62:65]
	v_mfma_f32_16x16x32_bf16 v[58:61], v[154:157], v[178:181], v[58:61]
	v_mfma_f32_16x16x32_bf16 v[46:49], v[142:145], v[186:189], v[46:49]
	v_mfma_f32_16x16x32_bf16 v[42:45], v[154:157], v[186:189], v[42:45]
	v_mfma_f32_16x16x32_bf16 v[30:33], v[142:145], v[194:197], v[30:33]
	v_mfma_f32_16x16x32_bf16 v[26:29], v[154:157], v[194:197], v[26:29]
	v_mfma_f32_16x16x32_bf16 v[14:17], v[142:145], v[202:205], v[14:17]
	v_mfma_f32_16x16x32_bf16 v[10:13], v[154:157], v[202:205], v[10:13]
	v_mfma_f32_16x16x32_bf16 v[62:65], v[150:153], v[182:185], v[62:65]
	v_mfma_f32_16x16x32_bf16 v[58:61], v[158:161], v[182:185], v[58:61]
	v_mfma_f32_16x16x32_bf16 v[46:49], v[150:153], v[190:193], v[46:49]
	v_mfma_f32_16x16x32_bf16 v[42:45], v[158:161], v[190:193], v[42:45]
	v_mfma_f32_16x16x32_bf16 v[30:33], v[150:153], v[198:201], v[30:33]
	v_mfma_f32_16x16x32_bf16 v[26:29], v[158:161], v[198:201], v[26:29]
	v_mfma_f32_16x16x32_bf16 v[14:17], v[150:153], v[206:209], v[14:17]
	v_mfma_f32_16x16x32_bf16 v[10:13], v[158:161], v[206:209], v[10:13]
	v_mfma_f32_16x16x32_bf16 v[54:57], v[162:165], v[178:181], v[54:57]
	v_mfma_f32_16x16x32_bf16 v[50:53], v[170:173], v[178:181], v[50:53]
	v_mfma_f32_16x16x32_bf16 v[38:41], v[162:165], v[186:189], v[38:41]
	v_mfma_f32_16x16x32_bf16 v[34:37], v[170:173], v[186:189], v[34:37]
	v_mfma_f32_16x16x32_bf16 v[22:25], v[162:165], v[194:197], v[22:25]
	v_mfma_f32_16x16x32_bf16 v[18:21], v[170:173], v[194:197], v[18:21]
	v_mfma_f32_16x16x32_bf16 v[6:9], v[162:165], v[202:205], v[6:9]
	v_mfma_f32_16x16x32_bf16 v[2:5], v[170:173], v[202:205], v[2:5]
	v_mfma_f32_16x16x32_bf16 v[54:57], v[166:169], v[182:185], v[54:57]
	v_mfma_f32_16x16x32_bf16 v[50:53], v[174:177], v[182:185], v[50:53]
	v_mfma_f32_16x16x32_bf16 v[38:41], v[166:169], v[190:193], v[38:41]
	v_mfma_f32_16x16x32_bf16 v[34:37], v[174:177], v[190:193], v[34:37]
	v_mfma_f32_16x16x32_bf16 v[22:25], v[166:169], v[198:201], v[22:25]
	v_mfma_f32_16x16x32_bf16 v[18:21], v[174:177], v[198:201], v[18:21]
	v_mfma_f32_16x16x32_bf16 v[6:9], v[166:169], v[206:209], v[6:9]
	v_mfma_f32_16x16x32_bf16 v[2:5], v[174:177], v[206:209], v[2:5]
	s_barrier
	s_add_i32 s94, s94, 2
	s_add_u32 s4, s4, 0x100
	s_addc_u32 s5, s5, 0
	s_add_u32 s15, s15, 0x100
	s_addc_u32 s21, s21, 0
	s_cmp_gt_u32 s94, 29
	s_cbranch_scc0 .LBB0_412
	s_and_b64 vcc, exec, s[12:13]
	s_cbranch_vccz .LBB0_415
	s_barrier

; #define PG8_STAGE(bufoff, gbase, voff) do { _Pragma("unroll") for (int _i = 0; _i < 2; ++_i) \
;         __builtin_amdgcn_global_load_lds((const unsigned*)((const char*)(gbase) + (voff)[_i]), (PG8_LAS unsigned*)(lds + (bufoff) + ldsw + _i * 8192), 16, 0, 0); } while (0)
; #define PG8_LDA(dst, b, h) do { _Pragma("unroll") for (int m = 0; m < 4; ++m) _Pragma("unroll") for (int k = 0; k < 2; ++k) dst[m][k] = *(const PG8_LAS bf16x8*)(lds + PG8_SA(b, h) + aoff + m * 2048 + k * 1024); } while (0)
; template <class Epi, class Sched, bool ALIGN_EPI = false, bool SP2 = false>
; __device__ __forceinline__ void gemm_phase(PG8_LAS unsigned char* lds, const Gemm g, const Sched& S, const Epi& E, int wave_s) {
;     ...
;         const char* nA = has_next ? (const char*)g.A + (size_t)nxt.pm * tstepA + (size_t)(nxt.pn / g.npg) * (size_t)(K * 2) : cA; const char* nB = has_next ? (const char*)g.Bt + (size_t)nxt.pn * tstepB : cB;
;         for (int t = 0; t < nt; t += 2) {
;             const bool last = (t == nt - 2);
;             const char* a1 = cA + (size_t)(t + 1) * kstep;
;             const char* a2 = last ? nA : cA + (size_t)(t + 2) * kstep; const char* b2 = last ? nB : cB + (size_t)(t + 2) * kstep;
;             const char* a3 = a2 + kstep; const char* b3 = b2 + kstep;
;             if (last && has_next) S.a_ready(nxt);
;             if constexpr (SP2) {
;             PG8_LDB(B0, 0, 0); PG8_LDB(B1, 0, 1); PG8_SCHED; PG8_LDA(At, 0, 0); PG8_STAGE(PG8_SA(1, 1), a1 + hstepA, voffA);
;             PG8_WAIT_V(8); PG8_WAIT_L(0); PG8_BAR; PG8_MMA(0, 0, At, B0); PG8_MMA(0, 1, At, B1); PG8_BAR; PG8_SCHED;
;             PG8_LDA(At, 0, 1); PG8_STAGE(PG8_SB(0, 0), b2, voffB); PG8_STAGE(PG8_SB(0, 1), b2 + hstepB, voffB); PG8_STAGE(PG8_SA(0, 0), a2, voffA);
;             PG8_WAIT_V(8); PG8_WAIT_L(0); PG8_BAR; PG8_MMA(1, 0, At, B0); PG8_MMA(1, 1, At, B1); PG8_BAR; PG8_SCHED;
;             PG8_LDB(B0, 1, 0); PG8_LDB(B1, 1, 1); PG8_SCHED; PG8_LDA(At, 1, 0); PG8_STAGE(PG8_SA(0, 1), a2 + hstepA, voffA);
;             PG8_WAIT_V(8); PG8_WAIT_L(0); PG8_BAR; PG8_MMA(0, 0, At, B0); PG8_MMA(0, 1, At, B1); PG8_BAR; PG8_SCHED;
;             PG8_LDA(At, 1, 1); PG8_STAGE(PG8_SB(1, 0), b3, voffB); PG8_STAGE(PG8_SB(1, 1), b3 + hstepB, voffB); PG8_STAGE(PG8_SA(1, 0), a3, voffA);
;             PG8_WAIT_V(8); PG8_WAIT_L(0); PG8_BAR; PG8_MMA(1, 0, At, B0); PG8_MMA(1, 1, At, B1); PG8_BAR; PG8_SCHED;
.LBB0_601:
	v_add_u32_e32 v228, 0x10000, v207
	v_add_u32_e32 v229, 0x14000, v207
	v_add_u32_e32 v230, 0x18000, v207
	v_add_u32_e32 v231, 0x1c000, v207
	s_ashr_i32 s21, s20, 31
	s_lshl_b64 s[2:3], s[20:21], 20
	s_add_u32 s88, s22, s2
	s_addc_u32 s89, s23, s3
	s_and_b64 s[2:3], s[4:5], exec
	s_cselect_b32 s2, s89, s31
	s_cselect_b32 s3, s88, s30
	s_add_u32 s4, s40, 0x80080
	s_addc_u32 s5, s41, 0
	s_add_u32 s21, s30, 0x100
	s_addc_u32 s27, s31, 0
	s_mov_b32 s81, -2
	s_add_u32 s30, s4, 0xfff80080
	s_addc_u32 s31, s5, -1
	s_add_i32 s84, 0, 0x10000
	s_cmp_eq_u32 s81, 28
	s_cselect_b32 s41, s29, s31
	s_cselect_b32 s40, s28, s30
	s_cselect_b32 s31, s2, s27
	s_cselect_b32 s30, s3, s21
	s_add_i32 s90, 0, 0x14000
	ds_read_b128 v[118:121], v228
	ds_read_b128 v[126:129], v228 offset:1024
	ds_read_b128 v[130:133], v228 offset:2048
	ds_read_b128 v[134:137], v228 offset:3072
	ds_read_b128 v[138:141], v229
	ds_read_b128 v[142:145], v229 offset:1024
	ds_read_b128 v[154:157], v229 offset:2048
	ds_read_b128 v[158:161], v229 offset:3072
	s_add_i32 m0, s35, 0xc000
	ds_read_b128 v[162:165], v208
	ds_read_b128 v[166:169], v208 offset:1024
	ds_read_b128 v[170:173], v208 offset:2048
	ds_read_b128 v[174:177], v208 offset:3072
	ds_read_b128 v[178:181], v208 offset:4096
	ds_read_b128 v[182:185], v208 offset:5120
	ds_read_b128 v[186:189], v208 offset:6144
	ds_read_b128 v[202:205], v208 offset:7168
	global_load_lds_dwordx4 v198, s[4:5]
	s_add_i32 m0, s35, 0xe000
	s_nop 0
	global_load_lds_dwordx4 v200, s[4:5]
	s_waitcnt vmcnt(8)
	s_waitcnt lgkmcnt(0)
	s_barrier
	s_waitcnt lgkmcnt(0)
	v_mfma_f32_16x16x32_bf16 v[150:153], v[118:121], v[162:165], 0
	v_mfma_f32_16x16x32_bf16 v[146:149], v[130:133], v[162:165], 0
	v_mfma_f32_16x16x32_bf16 v[110:113], v[118:121], v[170:173], 0
	v_mfma_f32_16x16x32_bf16 v[106:109], v[130:133], v[170:173], 0
	v_mfma_f32_16x16x32_bf16 v[94:97], v[118:121], v[178:181], 0
	v_mfma_f32_16x16x32_bf16 v[90:93], v[130:133], v[178:181], 0
	v_mfma_f32_16x16x32_bf16 v[78:81], v[118:121], v[186:189], 0
	v_mfma_f32_16x16x32_bf16 v[74:77], v[130:133], v[186:189], 0
	v_mfma_f32_16x16x32_bf16 v[150:153], v[126:129], v[166:169], v[150:153]
	v_mfma_f32_16x16x32_bf16 v[146:149], v[134:137], v[166:169], v[146:149]
	v_mfma_f32_16x16x32_bf16 v[110:113], v[126:129], v[174:177], v[110:113]
	v_mfma_f32_16x16x32_bf16 v[106:109], v[134:137], v[174:177], v[106:109]
	v_mfma_f32_16x16x32_bf16 v[94:97], v[126:129], v[182:185], v[94:97]
	v_mfma_f32_16x16x32_bf16 v[90:93], v[134:137], v[182:185], v[90:93]
	v_mfma_f32_16x16x32_bf16 v[78:81], v[126:129], v[202:205], v[78:81]
	v_mfma_f32_16x16x32_bf16 v[74:77], v[134:137], v[202:205], v[74:77]
	v_mfma_f32_16x16x32_bf16 v[122:125], v[138:141], v[162:165], 0
	v_mfma_f32_16x16x32_bf16 v[114:117], v[154:157], v[162:165], 0
	v_mfma_f32_16x16x32_bf16 v[102:105], v[138:141], v[170:173], 0
	v_mfma_f32_16x16x32_bf16 v[98:101], v[154:157], v[170:173], 0
	v_mfma_f32_16x16x32_bf16 v[86:89], v[138:141], v[178:181], 0
	v_mfma_f32_16x16x32_bf16 v[82:85], v[154:157], v[178:181], 0
	v_mfma_f32_16x16x32_bf16 v[70:73], v[138:141], v[186:189], 0
	v_mfma_f32_16x16x32_bf16 v[66:69], v[154:157], v[186:189], 0
	v_mfma_f32_16x16x32_bf16 v[122:125], v[142:145], v[166:169], v[122:125]
	v_mfma_f32_16x16x32_bf16 v[114:117], v[158:161], v[166:169], v[114:117]
	v_mfma_f32_16x16x32_bf16 v[102:105], v[142:145], v[174:177], v[102:105]
	v_mfma_f32_16x16x32_bf16 v[98:101], v[158:161], v[174:177], v[98:101]
	v_mfma_f32_16x16x32_bf16 v[86:89], v[142:145], v[182:185], v[86:89]
	v_mfma_f32_16x16x32_bf16 v[82:85], v[158:161], v[182:185], v[82:85]
	v_mfma_f32_16x16x32_bf16 v[70:73], v[142:145], v[202:205], v[70:73]
	v_mfma_f32_16x16x32_bf16 v[66:69], v[158:161], v[202:205], v[66:69]
	s_barrier
	s_add_i32 s84, s84, s34
	v_lshl_add_u64 v[210:211], s[30:31], 0, v[194:195]
	s_mov_b32 m0, s84
	ds_read_b128 v[162:165], v208 offset:16384
	ds_read_b128 v[166:169], v208 offset:17408
	ds_read_b128 v[170:173], v208 offset:18432
	ds_read_b128 v[174:177], v208 offset:19456
	ds_read_b128 v[178:181], v208 offset:20480
	ds_read_b128 v[182:185], v208 offset:21504
	ds_read_b128 v[186:189], v208 offset:22528
	ds_read_b128 v[202:205], v208 offset:23552
	global_load_lds_dwordx4 v[210:211], off
	s_add_i32 m0, s84, 0x2000
	s_add_u32 s84, s30, 0x80000
	v_lshl_add_u64 v[212:213], s[30:31], 0, v[190:191]
	s_addc_u32 s85, s31, 0
	s_add_i32 s90, s90, s34
	global_load_lds_dwordx4 v[212:213], off
	s_mov_b32 m0, s90
	v_lshl_add_u64 v[216:217], s[40:41], 0, v[192:193]
	global_load_lds_dwordx4 v194, s[84:85]
	s_add_i32 m0, s90, 0x2000
	s_nop 0
	global_load_lds_dwordx4 v190, s[84:85]
	v_lshl_add_u64 v[214:215], s[40:41], 0, v[196:197]
	s_mov_b32 m0, s35
	s_nop 0
	global_load_lds_dwordx4 v[214:215], off
	s_mov_b32 m0, s36
	s_nop 0
	global_load_lds_dwordx4 v[216:217], off
	s_waitcnt vmcnt(8)
	s_waitcnt lgkmcnt(0)
	s_barrier
; #define PG8_STAGE(bufoff, gbase, voff) do { _Pragma("unroll") for (int _i = 0; _i < 2; ++_i) \
;         __builtin_amdgcn_global_load_lds((const unsigned*)((const char*)(gbase) + (voff)[_i]), (PG8_LAS unsigned*)(lds + (bufoff) + ldsw + _i * 8192), 16, 0, 0); } while (0)
; #define PG8_LDA(dst, b, h) do { _Pragma("unroll") for (int m = 0; m < 4; ++m) _Pragma("unroll") for (int k = 0; k < 2; ++k) dst[m][k] = *(const PG8_LAS bf16x8*)(lds + PG8_SA(b, h) + aoff + m * 2048 + k * 1024); } while (0)
; #define PG8_LDB(dst, b, h) do { _Pragma("unroll") for (int n = 0; n < 2; ++n) _Pragma("unroll") for (int k = 0; k < 2; ++k) dst[n][k] = *(const PG8_LAS bf16x8*)(lds + PG8_SB(b, h) + boff + n * 2048 + k * 1024); } while (0)
; #define PG8_MMA(ai, bj, At, Bt) do { __builtin_amdgcn_s_setprio(1); _Pragma("unroll") for (int m = 0; m < 4; ++m) _Pragma("unroll") for (int n = 0; n < 2; ++n) _Pragma("unroll") for (int k = 0; k < 2; ++k) \
;         acc[ai][bj][m][n] = __builtin_amdgcn_mfma_f32_16x16x32_bf16(Bt[n][k], At[m][k], acc[ai][bj][m][n], 0, 0, 0); __builtin_amdgcn_s_setprio(0); } while (0)
; #define PG8_WAIT_V(n) asm volatile("s_waitcnt vmcnt(" #n ")" ::: "memory")
; #define PG8_WAIT_L(n) asm volatile("s_waitcnt lgkmcnt(" #n ")" ::: "memory")
; #define PG8_BAR __builtin_amdgcn_s_barrier()
; #define PG8_SCHED __builtin_amdgcn_sched_barrier(0)
; template <class Epi, class Sched, bool ALIGN_EPI = false, bool SP2 = false>
; __device__ __forceinline__ void gemm_phase(PG8_LAS unsigned char* lds, const Gemm g, const Sched& S, const Epi& E, int wave_s) {
;     ...
;             PG8_WAIT_V(8); PG8_WAIT_L(0); PG8_BAR; PG8_MMA(1, 0, At, B0); PG8_MMA(1, 1, At, B1); PG8_BAR; PG8_SCHED;
;             PG8_LDB(B0, 1, 0); PG8_LDB(B1, 1, 1); PG8_SCHED; PG8_LDA(At, 1, 0); PG8_STAGE(PG8_SA(0, 1), a2 + hstepA, voffA);
;             PG8_WAIT_V(8); PG8_WAIT_L(0); PG8_BAR; PG8_MMA(0, 0, At, B0); PG8_MMA(0, 1, At, B1); PG8_BAR; PG8_SCHED;
;             PG8_LDA(At, 1, 1); PG8_STAGE(PG8_SB(1, 0), b3, voffB); PG8_STAGE(PG8_SB(1, 1), b3 + hstepB, voffB); PG8_STAGE(PG8_SA(1, 0), a3, voffA);
;             PG8_WAIT_V(8); PG8_WAIT_L(0); PG8_BAR; PG8_MMA(1, 0, At, B0); PG8_MMA(1, 1, At, B1); PG8_BAR; PG8_SCHED;
	s_waitcnt lgkmcnt(0)
	v_mfma_f32_16x16x32_bf16 v[62:65], v[118:121], v[162:165], 0
	v_mfma_f32_16x16x32_bf16 v[58:61], v[130:133], v[162:165], 0
	v_mfma_f32_16x16x32_bf16 v[46:49], v[118:121], v[170:173], 0
	v_mfma_f32_16x16x32_bf16 v[42:45], v[130:133], v[170:173], 0
	v_mfma_f32_16x16x32_bf16 v[30:33], v[118:121], v[178:181], 0
	v_mfma_f32_16x16x32_bf16 v[26:29], v[130:133], v[178:181], 0
	v_mfma_f32_16x16x32_bf16 v[14:17], v[118:121], v[186:189], 0
	v_mfma_f32_16x16x32_bf16 v[10:13], v[130:133], v[186:189], 0
	v_mfma_f32_16x16x32_bf16 v[62:65], v[126:129], v[166:169], v[62:65]
	v_mfma_f32_16x16x32_bf16 v[58:61], v[134:137], v[166:169], v[58:61]
	v_mfma_f32_16x16x32_bf16 v[46:49], v[126:129], v[174:177], v[46:49]
	v_mfma_f32_16x16x32_bf16 v[42:45], v[134:137], v[174:177], v[42:45]
	v_mfma_f32_16x16x32_bf16 v[30:33], v[126:129], v[182:185], v[30:33]
	v_mfma_f32_16x16x32_bf16 v[26:29], v[134:137], v[182:185], v[26:29]
	v_mfma_f32_16x16x32_bf16 v[14:17], v[126:129], v[202:205], v[14:17]
	v_mfma_f32_16x16x32_bf16 v[10:13], v[134:137], v[202:205], v[10:13]
	v_mfma_f32_16x16x32_bf16 v[54:57], v[138:141], v[162:165], 0
	v_mfma_f32_16x16x32_bf16 v[50:53], v[154:157], v[162:165], 0
	v_mfma_f32_16x16x32_bf16 v[38:41], v[138:141], v[170:173], 0
	v_mfma_f32_16x16x32_bf16 v[34:37], v[154:157], v[170:173], 0
	v_mfma_f32_16x16x32_bf16 v[22:25], v[138:141], v[178:181], 0
	v_mfma_f32_16x16x32_bf16 v[18:21], v[154:157], v[178:181], 0
	v_mfma_f32_16x16x32_bf16 v[6:9], v[138:141], v[186:189], 0
	v_mfma_f32_16x16x32_bf16 v[2:5], v[154:157], v[186:189], 0
	v_mfma_f32_16x16x32_bf16 v[54:57], v[142:145], v[166:169], v[54:57]
	v_mfma_f32_16x16x32_bf16 v[50:53], v[158:161], v[166:169], v[50:53]
	v_mfma_f32_16x16x32_bf16 v[38:41], v[142:145], v[174:177], v[38:41]
	v_mfma_f32_16x16x32_bf16 v[34:37], v[158:161], v[174:177], v[34:37]
	v_mfma_f32_16x16x32_bf16 v[22:25], v[142:145], v[182:185], v[22:25]
	v_mfma_f32_16x16x32_bf16 v[18:21], v[158:161], v[182:185], v[18:21]
	v_mfma_f32_16x16x32_bf16 v[6:9], v[142:145], v[202:205], v[6:9]
	v_mfma_f32_16x16x32_bf16 v[2:5], v[158:161], v[202:205], v[2:5]
	s_barrier
	s_add_i32 s84, 0, 0x18000
	s_add_i32 s85, 0, 0x1c000
	ds_read_b128 v[118:121], v230
	ds_read_b128 v[126:129], v230 offset:1024
	ds_read_b128 v[130:133], v230 offset:2048
	ds_read_b128 v[134:137], v230 offset:3072
	ds_read_b128 v[138:141], v231
	ds_read_b128 v[142:145], v231 offset:1024
	ds_read_b128 v[154:157], v231 offset:2048
	ds_read_b128 v[158:161], v231 offset:3072
	s_add_u32 s40, s40, 0x80000
	s_addc_u32 s41, s41, 0
	s_mov_b32 m0, s37
	ds_read_b128 v[162:165], v208 offset:32768
	ds_read_b128 v[166:169], v208 offset:33792
	ds_read_b128 v[170:173], v208 offset:34816
	ds_read_b128 v[174:177], v208 offset:35840
	ds_read_b128 v[178:181], v208 offset:36864
	ds_read_b128 v[182:185], v208 offset:37888
	ds_read_b128 v[186:189], v208 offset:38912
	ds_read_b128 v[202:205], v208 offset:39936
	global_load_lds_dwordx4 v196, s[40:41]
	s_mov_b32 m0, s42
	s_nop 0
	global_load_lds_dwordx4 v192, s[40:41]
	s_waitcnt vmcnt(8)
	s_waitcnt lgkmcnt(0)
	s_barrier
	s_waitcnt lgkmcnt(0)
	v_mfma_f32_16x16x32_bf16 v[150:153], v[118:121], v[162:165], v[150:153]
	v_mfma_f32_16x16x32_bf16 v[146:149], v[130:133], v[162:165], v[146:149]
	v_mfma_f32_16x16x32_bf16 v[110:113], v[118:121], v[170:173], v[110:113]
	v_mfma_f32_16x16x32_bf16 v[106:109], v[130:133], v[170:173], v[106:109]
	v_mfma_f32_16x16x32_bf16 v[94:97], v[118:121], v[178:181], v[94:97]
	v_mfma_f32_16x16x32_bf16 v[90:93], v[130:133], v[178:181], v[90:93]
	v_mfma_f32_16x16x32_bf16 v[78:81], v[118:121], v[186:189], v[78:81]
	v_mfma_f32_16x16x32_bf16 v[74:77], v[130:133], v[186:189], v[74:77]
	v_mfma_f32_16x16x32_bf16 v[150:153], v[126:129], v[166:169], v[150:153]
	v_mfma_f32_16x16x32_bf16 v[146:149], v[134:137], v[166:169], v[146:149]
	v_mfma_f32_16x16x32_bf16 v[110:113], v[126:129], v[174:177], v[110:113]
	v_mfma_f32_16x16x32_bf16 v[106:109], v[134:137], v[174:177], v[106:109]
	v_mfma_f32_16x16x32_bf16 v[94:97], v[126:129], v[182:185], v[94:97]
	v_mfma_f32_16x16x32_bf16 v[90:93], v[134:137], v[182:185], v[90:93]
	v_mfma_f32_16x16x32_bf16 v[78:81], v[126:129], v[202:205], v[78:81]
	v_mfma_f32_16x16x32_bf16 v[74:77], v[134:137], v[202:205], v[74:77]
	v_mfma_f32_16x16x32_bf16 v[122:125], v[138:141], v[162:165], v[122:125]
	v_mfma_f32_16x16x32_bf16 v[114:117], v[154:157], v[162:165], v[114:117]
	v_mfma_f32_16x16x32_bf16 v[102:105], v[138:141], v[170:173], v[102:105]
	v_mfma_f32_16x16x32_bf16 v[98:101], v[154:157], v[170:173], v[98:101]
	v_mfma_f32_16x16x32_bf16 v[86:89], v[138:141], v[178:181], v[86:89]
	v_mfma_f32_16x16x32_bf16 v[82:85], v[154:157], v[178:181], v[82:85]
	v_mfma_f32_16x16x32_bf16 v[70:73], v[138:141], v[186:189], v[70:73]
	v_mfma_f32_16x16x32_bf16 v[66:69], v[154:157], v[186:189], v[66:69]
	v_mfma_f32_16x16x32_bf16 v[122:125], v[142:145], v[166:169], v[122:125]
	v_mfma_f32_16x16x32_bf16 v[114:117], v[158:161], v[166:169], v[114:117]
	v_mfma_f32_16x16x32_bf16 v[102:105], v[142:145], v[174:177], v[102:105]
	v_mfma_f32_16x16x32_bf16 v[98:101], v[158:161], v[174:177], v[98:101]
	v_mfma_f32_16x16x32_bf16 v[86:89], v[142:145], v[182:185], v[86:89]
	v_mfma_f32_16x16x32_bf16 v[82:85], v[158:161], v[182:185], v[82:85]
	v_mfma_f32_16x16x32_bf16 v[70:73], v[142:145], v[202:205], v[70:73]
	v_mfma_f32_16x16x32_bf16 v[66:69], v[158:161], v[202:205], v[66:69]
	s_barrier
; #define PG8_STAGE(bufoff, gbase, voff) do { _Pragma("unroll") for (int _i = 0; _i < 2; ++_i) \
;         __builtin_amdgcn_global_load_lds((const unsigned*)((const char*)(gbase) + (voff)[_i]), (PG8_LAS unsigned*)(lds + (bufoff) + ldsw + _i * 8192), 16, 0, 0); } while (0)
; #define PG8_LDA(dst, b, h) do { _Pragma("unroll") for (int m = 0; m < 4; ++m) _Pragma("unroll") for (int k = 0; k < 2; ++k) dst[m][k] = *(const PG8_LAS bf16x8*)(lds + PG8_SA(b, h) + aoff + m * 2048 + k * 1024); } while (0)
; #define PG8_LDB(dst, b, h) do { _Pragma("unroll") for (int n = 0; n < 2; ++n) _Pragma("unroll") for (int k = 0; k < 2; ++k) dst[n][k] = *(const PG8_LAS bf16x8*)(lds + PG8_SB(b, h) + boff + n * 2048 + k * 1024); } while (0)
; #define PG8_MMA(ai, bj, At, Bt) do { __builtin_amdgcn_s_setprio(1); _Pragma("unroll") for (int m = 0; m < 4; ++m) _Pragma("unroll") for (int n = 0; n < 2; ++n) _Pragma("unroll") for (int k = 0; k < 2; ++k) \
;         acc[ai][bj][m][n] = __builtin_amdgcn_mfma_f32_16x16x32_bf16(Bt[n][k], At[m][k], acc[ai][bj][m][n], 0, 0, 0); __builtin_amdgcn_s_setprio(0); } while (0)
; #define PG8_BAR __builtin_amdgcn_s_barrier()
; template <class Epi, class Sched, bool ALIGN_EPI = false, bool SP2 = false>
; __device__ __forceinline__ void gemm_phase(PG8_LAS unsigned char* lds, const Gemm g, const Sched& S, const Epi& E, int wave_s) {
;     ...
;             PG8_LDB(B0, 0, 0); PG8_LDB(B1, 0, 1); PG8_SCHED; PG8_LDA(At, 0, 0); PG8_STAGE(PG8_SA(1, 1), a1 + hstepA, voffA);
;             PG8_WAIT_V(8); PG8_WAIT_L(0); PG8_BAR; PG8_MMA(0, 0, At, B0); PG8_MMA(0, 1, At, B1); PG8_BAR; PG8_SCHED;
;             PG8_LDA(At, 0, 1); PG8_STAGE(PG8_SB(0, 0), b2, voffB); PG8_STAGE(PG8_SB(0, 1), b2 + hstepB, voffB); PG8_STAGE(PG8_SA(0, 0), a2, voffA);
;             PG8_WAIT_V(8); PG8_WAIT_L(0); PG8_BAR; PG8_MMA(1, 0, At, B0); PG8_MMA(1, 1, At, B1); PG8_BAR; PG8_SCHED;
;             PG8_LDB(B0, 1, 0); PG8_LDB(B1, 1, 1); PG8_SCHED; PG8_LDA(At, 1, 0); PG8_STAGE(PG8_SA(0, 1), a2 + hstepA, voffA);
;             PG8_WAIT_V(8); PG8_WAIT_L(0); PG8_BAR; PG8_MMA(0, 0, At, B0); PG8_MMA(0, 1, At, B1); PG8_BAR; PG8_SCHED;
;             PG8_LDA(At, 1, 1); PG8_STAGE(PG8_SB(1, 0), b3, voffB); PG8_STAGE(PG8_SB(1, 1), b3 + hstepB, voffB); PG8_STAGE(PG8_SA(1, 0), a3, voffA);
;             PG8_WAIT_V(8); PG8_WAIT_L(0); PG8_BAR; PG8_MMA(1, 0, At, B0); PG8_MMA(1, 1, At, B1); PG8_BAR; PG8_SCHED;
	s_add_i32 s40, s84, s34
	v_lshl_add_u64 v[210:211], v[210:211], 0, s[60:61]
	s_mov_b32 m0, s40
	ds_read_b128 v[162:165], v208 offset:49152
	ds_read_b128 v[166:169], v208 offset:50176
	ds_read_b128 v[170:173], v208 offset:51200
	ds_read_b128 v[174:177], v208 offset:52224
	ds_read_b128 v[178:181], v208 offset:53248
	ds_read_b128 v[182:185], v208 offset:54272
	ds_read_b128 v[186:189], v208 offset:55296
	ds_read_b128 v[202:205], v208 offset:56320
	global_load_lds_dwordx4 v[210:211], off
	s_add_i32 m0, s40, 0x2000
	s_add_u32 s30, s30, 0x80080
	v_lshl_add_u64 v[210:211], v[212:213], 0, s[60:61]
	s_addc_u32 s31, s31, 0
	s_add_i32 s40, s85, s34
	global_load_lds_dwordx4 v[210:211], off
	s_mov_b32 m0, s40
	s_nop 0
	global_load_lds_dwordx4 v194, s[30:31]
	s_add_i32 m0, s40, 0x2000
	s_nop 0
	global_load_lds_dwordx4 v190, s[30:31]
	v_lshl_add_u64 v[210:211], v[214:215], 0, s[60:61]
	s_mov_b32 m0, s46
	s_nop 0
	global_load_lds_dwordx4 v[210:211], off
	v_lshl_add_u64 v[210:211], v[216:217], 0, s[60:61]
	s_mov_b32 m0, s47
	s_nop 0
	global_load_lds_dwordx4 v[210:211], off
	s_waitcnt vmcnt(8)
	s_waitcnt lgkmcnt(0)
	s_barrier
	s_waitcnt lgkmcnt(0)
	v_mfma_f32_16x16x32_bf16 v[62:65], v[118:121], v[162:165], v[62:65]
	v_mfma_f32_16x16x32_bf16 v[58:61], v[130:133], v[162:165], v[58:61]
	v_mfma_f32_16x16x32_bf16 v[46:49], v[118:121], v[170:173], v[46:49]
	v_mfma_f32_16x16x32_bf16 v[42:45], v[130:133], v[170:173], v[42:45]
	v_mfma_f32_16x16x32_bf16 v[30:33], v[118:121], v[178:181], v[30:33]
	v_mfma_f32_16x16x32_bf16 v[26:29], v[130:133], v[178:181], v[26:29]
	v_mfma_f32_16x16x32_bf16 v[14:17], v[118:121], v[186:189], v[14:17]
	v_mfma_f32_16x16x32_bf16 v[10:13], v[130:133], v[186:189], v[10:13]
	v_mfma_f32_16x16x32_bf16 v[62:65], v[126:129], v[166:169], v[62:65]
	v_mfma_f32_16x16x32_bf16 v[58:61], v[134:137], v[166:169], v[58:61]
	v_mfma_f32_16x16x32_bf16 v[46:49], v[126:129], v[174:177], v[46:49]
	v_mfma_f32_16x16x32_bf16 v[42:45], v[134:137], v[174:177], v[42:45]
	v_mfma_f32_16x16x32_bf16 v[30:33], v[126:129], v[182:185], v[30:33]
	v_mfma_f32_16x16x32_bf16 v[26:29], v[134:137], v[182:185], v[26:29]
	v_mfma_f32_16x16x32_bf16 v[14:17], v[126:129], v[202:205], v[14:17]
	v_mfma_f32_16x16x32_bf16 v[10:13], v[134:137], v[202:205], v[10:13]
	v_mfma_f32_16x16x32_bf16 v[54:57], v[138:141], v[162:165], v[54:57]
	v_mfma_f32_16x16x32_bf16 v[50:53], v[154:157], v[162:165], v[50:53]
	v_mfma_f32_16x16x32_bf16 v[38:41], v[138:141], v[170:173], v[38:41]
	v_mfma_f32_16x16x32_bf16 v[34:37], v[154:157], v[170:173], v[34:37]
	v_mfma_f32_16x16x32_bf16 v[22:25], v[138:141], v[178:181], v[22:25]
	v_mfma_f32_16x16x32_bf16 v[18:21], v[154:157], v[178:181], v[18:21]
	v_mfma_f32_16x16x32_bf16 v[6:9], v[138:141], v[186:189], v[6:9]
	v_mfma_f32_16x16x32_bf16 v[2:5], v[154:157], v[186:189], v[2:5]
	v_mfma_f32_16x16x32_bf16 v[54:57], v[142:145], v[166:169], v[54:57]
	v_mfma_f32_16x16x32_bf16 v[50:53], v[158:161], v[166:169], v[50:53]
	v_mfma_f32_16x16x32_bf16 v[38:41], v[142:145], v[174:177], v[38:41]
	v_mfma_f32_16x16x32_bf16 v[34:37], v[158:161], v[174:177], v[34:37]
	v_mfma_f32_16x16x32_bf16 v[22:25], v[142:145], v[182:185], v[22:25]
	v_mfma_f32_16x16x32_bf16 v[18:21], v[158:161], v[182:185], v[18:21]
	v_mfma_f32_16x16x32_bf16 v[6:9], v[142:145], v[202:205], v[6:9]
	v_mfma_f32_16x16x32_bf16 v[2:5], v[158:161], v[202:205], v[2:5]
	s_barrier
	s_add_i32 s81, s81, 2
	s_add_u32 s4, s4, 0x100
	s_addc_u32 s5, s5, 0
	s_add_u32 s21, s21, 0x100
	s_addc_u32 s27, s27, 0
	s_cmp_gt_u32 s81, 29
.LBB0_602:
	s_add_u32 s30, s4, 0xfff80080
	s_addc_u32 s31, s5, -1
	s_add_i32 s84, 0, 0x10000
	s_cmp_eq_u32 s81, 28
	s_cselect_b32 s41, s29, s31
	s_cselect_b32 s40, s28, s30
	s_cselect_b32 s31, s2, s27
	s_cselect_b32 s30, s3, s21
	s_add_i32 s90, 0, 0x14000
	ds_read_b128 v[118:121], v228
	ds_read_b128 v[126:129], v228 offset:1024
	ds_read_b128 v[130:133], v228 offset:2048
	ds_read_b128 v[134:137], v228 offset:3072
	ds_read_b128 v[138:141], v229
	ds_read_b128 v[142:145], v229 offset:1024
	ds_read_b128 v[154:157], v229 offset:2048
	ds_read_b128 v[158:161], v229 offset:3072
	s_add_i32 m0, s35, 0xc000
	ds_read_b128 v[162:165], v208
	ds_read_b128 v[166:169], v208 offset:1024
	ds_read_b128 v[170:173], v208 offset:2048
	ds_read_b128 v[174:177], v208 offset:3072
	ds_read_b128 v[178:181], v208 offset:4096
	ds_read_b128 v[182:185], v208 offset:5120
	ds_read_b128 v[186:189], v208 offset:6144
	ds_read_b128 v[202:205], v208 offset:7168
	global_load_lds_dwordx4 v198, s[4:5]
	s_add_i32 m0, s35, 0xe000
	s_nop 0
	global_load_lds_dwordx4 v200, s[4:5]
	s_waitcnt vmcnt(8)
	s_waitcnt lgkmcnt(0)
	s_barrier
; #define PG8_STAGE(bufoff, gbase, voff) do { _Pragma("unroll") for (int _i = 0; _i < 2; ++_i) \
;         __builtin_amdgcn_global_load_lds((const unsigned*)((const char*)(gbase) + (voff)[_i]), (PG8_LAS unsigned*)(lds + (bufoff) + ldsw + _i * 8192), 16, 0, 0); } while (0)
; #define PG8_LDA(dst, b, h) do { _Pragma("unroll") for (int m = 0; m < 4; ++m) _Pragma("unroll") for (int k = 0; k < 2; ++k) dst[m][k] = *(const PG8_LAS bf16x8*)(lds + PG8_SA(b, h) + aoff + m * 2048 + k * 1024); } while (0)
; #define PG8_LDB(dst, b, h) do { _Pragma("unroll") for (int n = 0; n < 2; ++n) _Pragma("unroll") for (int k = 0; k < 2; ++k) dst[n][k] = *(const PG8_LAS bf16x8*)(lds + PG8_SB(b, h) + boff + n * 2048 + k * 1024); } while (0)
; #define PG8_MMA(ai, bj, At, Bt) do { __builtin_amdgcn_s_setprio(1); _Pragma("unroll") for (int m = 0; m < 4; ++m) _Pragma("unroll") for (int n = 0; n < 2; ++n) _Pragma("unroll") for (int k = 0; k < 2; ++k) \
;         acc[ai][bj][m][n] = __builtin_amdgcn_mfma_f32_16x16x32_bf16(Bt[n][k], At[m][k], acc[ai][bj][m][n], 0, 0, 0); __builtin_amdgcn_s_setprio(0); } while (0)
; #define PG8_WAIT_V(n) asm volatile("s_waitcnt vmcnt(" #n ")" ::: "memory")
; #define PG8_WAIT_L(n) asm volatile("s_waitcnt lgkmcnt(" #n ")" ::: "memory")
; #define PG8_BAR __builtin_amdgcn_s_barrier()
; #define PG8_SCHED __builtin_amdgcn_sched_barrier(0)
; template <class Epi, class Sched, bool ALIGN_EPI = false, bool SP2 = false>
; __device__ __forceinline__ void gemm_phase(PG8_LAS unsigned char* lds, const Gemm g, const Sched& S, const Epi& E, int wave_s) {
;     ...
;             PG8_WAIT_V(8); PG8_WAIT_L(0); PG8_BAR; PG8_MMA(0, 0, At, B0); PG8_MMA(0, 1, At, B1); PG8_BAR; PG8_SCHED;
;             PG8_LDA(At, 0, 1); PG8_STAGE(PG8_SB(0, 0), b2, voffB); PG8_STAGE(PG8_SB(0, 1), b2 + hstepB, voffB); PG8_STAGE(PG8_SA(0, 0), a2, voffA);
;             PG8_WAIT_V(8); PG8_WAIT_L(0); PG8_BAR; PG8_MMA(1, 0, At, B0); PG8_MMA(1, 1, At, B1); PG8_BAR; PG8_SCHED;
;             PG8_LDB(B0, 1, 0); PG8_LDB(B1, 1, 1); PG8_SCHED; PG8_LDA(At, 1, 0); PG8_STAGE(PG8_SA(0, 1), a2 + hstepA, voffA);
;             PG8_WAIT_V(8); PG8_WAIT_L(0); PG8_BAR; PG8_MMA(0, 0, At, B0); PG8_MMA(0, 1, At, B1); PG8_BAR; PG8_SCHED;
	s_waitcnt lgkmcnt(0)
	v_mfma_f32_16x16x32_bf16 v[150:153], v[118:121], v[162:165], v[150:153]
	v_mfma_f32_16x16x32_bf16 v[146:149], v[130:133], v[162:165], v[146:149]
	v_mfma_f32_16x16x32_bf16 v[110:113], v[118:121], v[170:173], v[110:113]
	v_mfma_f32_16x16x32_bf16 v[106:109], v[130:133], v[170:173], v[106:109]
	v_mfma_f32_16x16x32_bf16 v[94:97], v[118:121], v[178:181], v[94:97]
	v_mfma_f32_16x16x32_bf16 v[90:93], v[130:133], v[178:181], v[90:93]
	v_mfma_f32_16x16x32_bf16 v[78:81], v[118:121], v[186:189], v[78:81]
	v_mfma_f32_16x16x32_bf16 v[74:77], v[130:133], v[186:189], v[74:77]
	v_mfma_f32_16x16x32_bf16 v[150:153], v[126:129], v[166:169], v[150:153]
	v_mfma_f32_16x16x32_bf16 v[146:149], v[134:137], v[166:169], v[146:149]
	v_mfma_f32_16x16x32_bf16 v[110:113], v[126:129], v[174:177], v[110:113]
	v_mfma_f32_16x16x32_bf16 v[106:109], v[134:137], v[174:177], v[106:109]
	v_mfma_f32_16x16x32_bf16 v[94:97], v[126:129], v[182:185], v[94:97]
	v_mfma_f32_16x16x32_bf16 v[90:93], v[134:137], v[182:185], v[90:93]
	v_mfma_f32_16x16x32_bf16 v[78:81], v[126:129], v[202:205], v[78:81]
	v_mfma_f32_16x16x32_bf16 v[74:77], v[134:137], v[202:205], v[74:77]
	v_mfma_f32_16x16x32_bf16 v[122:125], v[138:141], v[162:165], v[122:125]
	v_mfma_f32_16x16x32_bf16 v[114:117], v[154:157], v[162:165], v[114:117]
	v_mfma_f32_16x16x32_bf16 v[102:105], v[138:141], v[170:173], v[102:105]
	v_mfma_f32_16x16x32_bf16 v[98:101], v[154:157], v[170:173], v[98:101]
	v_mfma_f32_16x16x32_bf16 v[86:89], v[138:141], v[178:181], v[86:89]
	v_mfma_f32_16x16x32_bf16 v[82:85], v[154:157], v[178:181], v[82:85]
	v_mfma_f32_16x16x32_bf16 v[70:73], v[138:141], v[186:189], v[70:73]
	v_mfma_f32_16x16x32_bf16 v[66:69], v[154:157], v[186:189], v[66:69]
	v_mfma_f32_16x16x32_bf16 v[122:125], v[142:145], v[166:169], v[122:125]
	v_mfma_f32_16x16x32_bf16 v[114:117], v[158:161], v[166:169], v[114:117]
	v_mfma_f32_16x16x32_bf16 v[102:105], v[142:145], v[174:177], v[102:105]
	v_mfma_f32_16x16x32_bf16 v[98:101], v[158:161], v[174:177], v[98:101]
	v_mfma_f32_16x16x32_bf16 v[86:89], v[142:145], v[182:185], v[86:89]
	v_mfma_f32_16x16x32_bf16 v[82:85], v[158:161], v[182:185], v[82:85]
	v_mfma_f32_16x16x32_bf16 v[70:73], v[142:145], v[202:205], v[70:73]
	v_mfma_f32_16x16x32_bf16 v[66:69], v[158:161], v[202:205], v[66:69]
	s_barrier
	s_add_i32 s84, s84, s34
	v_lshl_add_u64 v[210:211], s[30:31], 0, v[194:195]
	s_mov_b32 m0, s84
	ds_read_b128 v[162:165], v208 offset:16384
	ds_read_b128 v[166:169], v208 offset:17408
	ds_read_b128 v[170:173], v208 offset:18432
	ds_read_b128 v[174:177], v208 offset:19456
	ds_read_b128 v[178:181], v208 offset:20480
	ds_read_b128 v[182:185], v208 offset:21504
	ds_read_b128 v[186:189], v208 offset:22528
	ds_read_b128 v[202:205], v208 offset:23552
	global_load_lds_dwordx4 v[210:211], off
	s_add_i32 m0, s84, 0x2000
	s_add_u32 s84, s30, 0x80000
	v_lshl_add_u64 v[212:213], s[30:31], 0, v[190:191]
	s_addc_u32 s85, s31, 0
	s_add_i32 s90, s90, s34
	global_load_lds_dwordx4 v[212:213], off
	s_mov_b32 m0, s90
	v_lshl_add_u64 v[216:217], s[40:41], 0, v[192:193]
	global_load_lds_dwordx4 v194, s[84:85]
	s_add_i32 m0, s90, 0x2000
	s_nop 0
	global_load_lds_dwordx4 v190, s[84:85]
	v_lshl_add_u64 v[214:215], s[40:41], 0, v[196:197]
	s_mov_b32 m0, s35
	s_nop 0
	global_load_lds_dwordx4 v[214:215], off
	s_mov_b32 m0, s36
	s_nop 0
	global_load_lds_dwordx4 v[216:217], off
	s_waitcnt vmcnt(8)
	s_waitcnt lgkmcnt(0)
	s_barrier
	s_waitcnt lgkmcnt(0)
	v_mfma_f32_16x16x32_bf16 v[62:65], v[118:121], v[162:165], v[62:65]
	v_mfma_f32_16x16x32_bf16 v[58:61], v[130:133], v[162:165], v[58:61]
	v_mfma_f32_16x16x32_bf16 v[46:49], v[118:121], v[170:173], v[46:49]
	v_mfma_f32_16x16x32_bf16 v[42:45], v[130:133], v[170:173], v[42:45]
	v_mfma_f32_16x16x32_bf16 v[30:33], v[118:121], v[178:181], v[30:33]
	v_mfma_f32_16x16x32_bf16 v[26:29], v[130:133], v[178:181], v[26:29]
	v_mfma_f32_16x16x32_bf16 v[14:17], v[118:121], v[186:189], v[14:17]
	v_mfma_f32_16x16x32_bf16 v[10:13], v[130:133], v[186:189], v[10:13]
	v_mfma_f32_16x16x32_bf16 v[62:65], v[126:129], v[166:169], v[62:65]
	v_mfma_f32_16x16x32_bf16 v[58:61], v[134:137], v[166:169], v[58:61]
	v_mfma_f32_16x16x32_bf16 v[46:49], v[126:129], v[174:177], v[46:49]
	v_mfma_f32_16x16x32_bf16 v[42:45], v[134:137], v[174:177], v[42:45]
	v_mfma_f32_16x16x32_bf16 v[30:33], v[126:129], v[182:185], v[30:33]
	v_mfma_f32_16x16x32_bf16 v[26:29], v[134:137], v[182:185], v[26:29]
	v_mfma_f32_16x16x32_bf16 v[14:17], v[126:129], v[202:205], v[14:17]
	v_mfma_f32_16x16x32_bf16 v[10:13], v[134:137], v[202:205], v[10:13]
	v_mfma_f32_16x16x32_bf16 v[54:57], v[138:141], v[162:165], v[54:57]
	v_mfma_f32_16x16x32_bf16 v[50:53], v[154:157], v[162:165], v[50:53]
	v_mfma_f32_16x16x32_bf16 v[38:41], v[138:141], v[170:173], v[38:41]
	v_mfma_f32_16x16x32_bf16 v[34:37], v[154:157], v[170:173], v[34:37]
	v_mfma_f32_16x16x32_bf16 v[22:25], v[138:141], v[178:181], v[22:25]
	v_mfma_f32_16x16x32_bf16 v[18:21], v[154:157], v[178:181], v[18:21]
	v_mfma_f32_16x16x32_bf16 v[6:9], v[138:141], v[186:189], v[6:9]
	v_mfma_f32_16x16x32_bf16 v[2:5], v[154:157], v[186:189], v[2:5]
	v_mfma_f32_16x16x32_bf16 v[54:57], v[142:145], v[166:169], v[54:57]
	v_mfma_f32_16x16x32_bf16 v[50:53], v[158:161], v[166:169], v[50:53]
	v_mfma_f32_16x16x32_bf16 v[38:41], v[142:145], v[174:177], v[38:41]
	v_mfma_f32_16x16x32_bf16 v[34:37], v[158:161], v[174:177], v[34:37]
	v_mfma_f32_16x16x32_bf16 v[22:25], v[142:145], v[182:185], v[22:25]
	v_mfma_f32_16x16x32_bf16 v[18:21], v[158:161], v[182:185], v[18:21]
	v_mfma_f32_16x16x32_bf16 v[6:9], v[142:145], v[202:205], v[6:9]
	v_mfma_f32_16x16x32_bf16 v[2:5], v[158:161], v[202:205], v[2:5]
	s_barrier
; #define PG8_STAGE(bufoff, gbase, voff) do { _Pragma("unroll") for (int _i = 0; _i < 2; ++_i) \
;         __builtin_amdgcn_global_load_lds((const unsigned*)((const char*)(gbase) + (voff)[_i]), (PG8_LAS unsigned*)(lds + (bufoff) + ldsw + _i * 8192), 16, 0, 0); } while (0)
; #define PG8_LDA(dst, b, h) do { _Pragma("unroll") for (int m = 0; m < 4; ++m) _Pragma("unroll") for (int k = 0; k < 2; ++k) dst[m][k] = *(const PG8_LAS bf16x8*)(lds + PG8_SA(b, h) + aoff + m * 2048 + k * 1024); } while (0)
; #define PG8_LDB(dst, b, h) do { _Pragma("unroll") for (int n = 0; n < 2; ++n) _Pragma("unroll") for (int k = 0; k < 2; ++k) dst[n][k] = *(const PG8_LAS bf16x8*)(lds + PG8_SB(b, h) + boff + n * 2048 + k * 1024); } while (0)
; #define PG8_MMA(ai, bj, At, Bt) do { __builtin_amdgcn_s_setprio(1); _Pragma("unroll") for (int m = 0; m < 4; ++m) _Pragma("unroll") for (int n = 0; n < 2; ++n) _Pragma("unroll") for (int k = 0; k < 2; ++k) \
;         acc[ai][bj][m][n] = __builtin_amdgcn_mfma_f32_16x16x32_bf16(Bt[n][k], At[m][k], acc[ai][bj][m][n], 0, 0, 0); __builtin_amdgcn_s_setprio(0); } while (0)
; #define PG8_WAIT_V(n) asm volatile("s_waitcnt vmcnt(" #n ")" ::: "memory")
; #define PG8_WAIT_L(n) asm volatile("s_waitcnt lgkmcnt(" #n ")" ::: "memory")
; #define PG8_BAR __builtin_amdgcn_s_barrier()
; #define PG8_SCHED __builtin_amdgcn_sched_barrier(0)
; template <class Epi, class Sched, bool ALIGN_EPI = false, bool SP2 = false>
; __device__ __forceinline__ void gemm_phase(PG8_LAS unsigned char* lds, const Gemm g, const Sched& S, const Epi& E, int wave_s) {
;     ...
;             PG8_LDB(B0, 1, 0); PG8_LDB(B1, 1, 1); PG8_SCHED; PG8_LDA(At, 1, 0); PG8_STAGE(PG8_SA(0, 1), a2 + hstepA, voffA);
;             PG8_WAIT_V(8); PG8_WAIT_L(0); PG8_BAR; PG8_MMA(0, 0, At, B0); PG8_MMA(0, 1, At, B1); PG8_BAR; PG8_SCHED;
;             PG8_LDA(At, 1, 1); PG8_STAGE(PG8_SB(1, 0), b3, voffB); PG8_STAGE(PG8_SB(1, 1), b3 + hstepB, voffB); PG8_STAGE(PG8_SA(1, 0), a3, voffA);
;             PG8_WAIT_V(8); PG8_WAIT_L(0); PG8_BAR; PG8_MMA(1, 0, At, B0); PG8_MMA(1, 1, At, B1); PG8_BAR; PG8_SCHED;
	s_add_i32 s84, 0, 0x18000
	s_add_i32 s85, 0, 0x1c000
	ds_read_b128 v[118:121], v230
	ds_read_b128 v[126:129], v230 offset:1024
	ds_read_b128 v[130:133], v230 offset:2048
	ds_read_b128 v[134:137], v230 offset:3072
	ds_read_b128 v[138:141], v231
	ds_read_b128 v[142:145], v231 offset:1024
	ds_read_b128 v[154:157], v231 offset:2048
	ds_read_b128 v[158:161], v231 offset:3072
	s_add_u32 s40, s40, 0x80000
	s_addc_u32 s41, s41, 0
	s_mov_b32 m0, s37
	ds_read_b128 v[162:165], v208 offset:32768
	ds_read_b128 v[166:169], v208 offset:33792
	ds_read_b128 v[170:173], v208 offset:34816
	ds_read_b128 v[174:177], v208 offset:35840
	ds_read_b128 v[178:181], v208 offset:36864
	ds_read_b128 v[182:185], v208 offset:37888
	ds_read_b128 v[186:189], v208 offset:38912
	ds_read_b128 v[202:205], v208 offset:39936
	global_load_lds_dwordx4 v196, s[40:41]
	v_lshl_add_u64 v[218:219], s[40:41], 0, v[192:193]
	s_mov_b32 m0, s42
	s_nop 0
	global_load_lds_dwordx4 v[218:219], off
	s_waitcnt vmcnt(8)
	s_waitcnt lgkmcnt(0)
	s_barrier
	s_waitcnt lgkmcnt(0)
	v_mfma_f32_16x16x32_bf16 v[150:153], v[118:121], v[162:165], v[150:153]
	v_mfma_f32_16x16x32_bf16 v[146:149], v[130:133], v[162:165], v[146:149]
	v_mfma_f32_16x16x32_bf16 v[110:113], v[118:121], v[170:173], v[110:113]
	v_mfma_f32_16x16x32_bf16 v[106:109], v[130:133], v[170:173], v[106:109]
	v_mfma_f32_16x16x32_bf16 v[94:97], v[118:121], v[178:181], v[94:97]
	v_mfma_f32_16x16x32_bf16 v[90:93], v[130:133], v[178:181], v[90:93]
	v_mfma_f32_16x16x32_bf16 v[78:81], v[118:121], v[186:189], v[78:81]
	v_mfma_f32_16x16x32_bf16 v[74:77], v[130:133], v[186:189], v[74:77]
	v_mfma_f32_16x16x32_bf16 v[150:153], v[126:129], v[166:169], v[150:153]
	v_mfma_f32_16x16x32_bf16 v[146:149], v[134:137], v[166:169], v[146:149]
	v_mfma_f32_16x16x32_bf16 v[110:113], v[126:129], v[174:177], v[110:113]
	v_mfma_f32_16x16x32_bf16 v[106:109], v[134:137], v[174:177], v[106:109]
	v_mfma_f32_16x16x32_bf16 v[94:97], v[126:129], v[182:185], v[94:97]
	v_mfma_f32_16x16x32_bf16 v[90:93], v[134:137], v[182:185], v[90:93]
	v_mfma_f32_16x16x32_bf16 v[78:81], v[126:129], v[202:205], v[78:81]
	v_mfma_f32_16x16x32_bf16 v[74:77], v[134:137], v[202:205], v[74:77]
	v_mfma_f32_16x16x32_bf16 v[122:125], v[138:141], v[162:165], v[122:125]
	v_mfma_f32_16x16x32_bf16 v[114:117], v[154:157], v[162:165], v[114:117]
	v_mfma_f32_16x16x32_bf16 v[102:105], v[138:141], v[170:173], v[102:105]
	v_mfma_f32_16x16x32_bf16 v[98:101], v[154:157], v[170:173], v[98:101]
	v_mfma_f32_16x16x32_bf16 v[86:89], v[138:141], v[178:181], v[86:89]
	v_mfma_f32_16x16x32_bf16 v[82:85], v[154:157], v[178:181], v[82:85]
	v_mfma_f32_16x16x32_bf16 v[70:73], v[138:141], v[186:189], v[70:73]
	v_mfma_f32_16x16x32_bf16 v[66:69], v[154:157], v[186:189], v[66:69]
	v_mfma_f32_16x16x32_bf16 v[122:125], v[142:145], v[166:169], v[122:125]
	v_mfma_f32_16x16x32_bf16 v[114:117], v[158:161], v[166:169], v[114:117]
	v_mfma_f32_16x16x32_bf16 v[102:105], v[142:145], v[174:177], v[102:105]
	v_mfma_f32_16x16x32_bf16 v[98:101], v[158:161], v[174:177], v[98:101]
	v_mfma_f32_16x16x32_bf16 v[86:89], v[142:145], v[182:185], v[86:89]
	v_mfma_f32_16x16x32_bf16 v[82:85], v[158:161], v[182:185], v[82:85]
	v_mfma_f32_16x16x32_bf16 v[70:73], v[142:145], v[202:205], v[70:73]
	v_mfma_f32_16x16x32_bf16 v[66:69], v[158:161], v[202:205], v[66:69]
	s_barrier
	s_add_i32 s40, s84, s34
	v_lshl_add_u64 v[210:211], v[210:211], 0, s[60:61]
	s_mov_b32 m0, s40
	ds_read_b128 v[162:165], v208 offset:49152
	ds_read_b128 v[166:169], v208 offset:50176
	ds_read_b128 v[170:173], v208 offset:51200
	ds_read_b128 v[174:177], v208 offset:52224
	ds_read_b128 v[178:181], v208 offset:53248
	ds_read_b128 v[182:185], v208 offset:54272
	ds_read_b128 v[186:189], v208 offset:55296
	ds_read_b128 v[202:205], v208 offset:56320
	global_load_lds_dwordx4 v[210:211], off
	s_add_i32 m0, s40, 0x2000
	s_add_u32 s30, s30, 0x80080
	v_lshl_add_u64 v[210:211], v[212:213], 0, s[60:61]
	s_addc_u32 s31, s31, 0
	s_add_i32 s40, s85, s34
	global_load_lds_dwordx4 v[210:211], off
	s_mov_b32 m0, s40
	s_nop 0
	global_load_lds_dwordx4 v194, s[30:31]
	s_add_i32 m0, s40, 0x2000
	s_nop 0
	global_load_lds_dwordx4 v190, s[30:31]
	v_lshl_add_u64 v[210:211], v[214:215], 0, s[60:61]
	s_mov_b32 m0, s46
	s_nop 0
	global_load_lds_dwordx4 v[210:211], off
	v_lshl_add_u64 v[210:211], v[216:217], 0, s[60:61]
	s_mov_b32 m0, s47
	s_nop 0
	global_load_lds_dwordx4 v[210:211], off
	s_waitcnt vmcnt(8)
	s_waitcnt lgkmcnt(0)
	s_barrier
	s_waitcnt lgkmcnt(0)
	v_mfma_f32_16x16x32_bf16 v[62:65], v[118:121], v[162:165], v[62:65]
	v_mfma_f32_16x16x32_bf16 v[58:61], v[130:133], v[162:165], v[58:61]
	v_mfma_f32_16x16x32_bf16 v[46:49], v[118:121], v[170:173], v[46:49]
	v_mfma_f32_16x16x32_bf16 v[42:45], v[130:133], v[170:173], v[42:45]
	v_mfma_f32_16x16x32_bf16 v[30:33], v[118:121], v[178:181], v[30:33]
	v_mfma_f32_16x16x32_bf16 v[26:29], v[130:133], v[178:181], v[26:29]
	v_mfma_f32_16x16x32_bf16 v[14:17], v[118:121], v[186:189], v[14:17]
	v_mfma_f32_16x16x32_bf16 v[10:13], v[130:133], v[186:189], v[10:13]
	v_mfma_f32_16x16x32_bf16 v[62:65], v[126:129], v[166:169], v[62:65]
	v_mfma_f32_16x16x32_bf16 v[58:61], v[134:137], v[166:169], v[58:61]
	v_mfma_f32_16x16x32_bf16 v[46:49], v[126:129], v[174:177], v[46:49]
	v_mfma_f32_16x16x32_bf16 v[42:45], v[134:137], v[174:177], v[42:45]
	v_mfma_f32_16x16x32_bf16 v[30:33], v[126:129], v[182:185], v[30:33]
	v_mfma_f32_16x16x32_bf16 v[26:29], v[134:137], v[182:185], v[26:29]
	v_mfma_f32_16x16x32_bf16 v[14:17], v[126:129], v[202:205], v[14:17]
	v_mfma_f32_16x16x32_bf16 v[10:13], v[134:137], v[202:205], v[10:13]
	v_mfma_f32_16x16x32_bf16 v[54:57], v[138:141], v[162:165], v[54:57]
	v_mfma_f32_16x16x32_bf16 v[50:53], v[154:157], v[162:165], v[50:53]
	v_mfma_f32_16x16x32_bf16 v[38:41], v[138:141], v[170:173], v[38:41]
	v_mfma_f32_16x16x32_bf16 v[34:37], v[154:157], v[170:173], v[34:37]
	v_mfma_f32_16x16x32_bf16 v[22:25], v[138:141], v[178:181], v[22:25]
	v_mfma_f32_16x16x32_bf16 v[18:21], v[154:157], v[178:181], v[18:21]
	v_mfma_f32_16x16x32_bf16 v[6:9], v[138:141], v[186:189], v[6:9]
	v_mfma_f32_16x16x32_bf16 v[2:5], v[154:157], v[186:189], v[2:5]
	v_mfma_f32_16x16x32_bf16 v[54:57], v[142:145], v[166:169], v[54:57]
	v_mfma_f32_16x16x32_bf16 v[50:53], v[158:161], v[166:169], v[50:53]
	v_mfma_f32_16x16x32_bf16 v[38:41], v[142:145], v[174:177], v[38:41]
	v_mfma_f32_16x16x32_bf16 v[34:37], v[158:161], v[174:177], v[34:37]
	v_mfma_f32_16x16x32_bf16 v[22:25], v[142:145], v[182:185], v[22:25]
	v_mfma_f32_16x16x32_bf16 v[18:21], v[158:161], v[182:185], v[18:21]
	v_mfma_f32_16x16x32_bf16 v[6:9], v[142:145], v[202:205], v[6:9]
	v_mfma_f32_16x16x32_bf16 v[2:5], v[158:161], v[202:205], v[2:5]
	s_barrier
	s_add_i32 s81, s81, 2
	s_add_u32 s4, s4, 0x100
	s_addc_u32 s5, s5, 0
	s_add_u32 s21, s21, 0x100
	s_addc_u32 s27, s27, 0
	s_cmp_gt_u32 s81, 29
	s_cbranch_scc0 .LBB0_602
	s_and_b64 vcc, exec, s[14:15]
	s_cbranch_vccz .LBB0_605
	s_barrier
